# fn_b steady-state interleaved K loop with counted vmcnt; scan att-chain LDS prefetch; gemm_out epilogue gate loads hoisted out of the store loop
# speedup vs baseline: 1.0317x; 1.0154x over previous
.LBB0_1057:
	ds_read_b128 v[108:111], v172 offset:32768
	ds_read_b128 v[112:115], v172 offset:32800
	ds_read_b128 v[116:119], v172 offset:32832
	ds_read_b128 v[128:131], v172 offset:32864
	ds_read_b128 v[120:123], v172 offset:32896
	ds_read_b128 v[124:127], v172 offset:32928
	ds_read_b128 v[132:135], v172 offset:32960
	ds_read_b128 v[136:139], v172 offset:32992
	s_waitcnt lgkmcnt(4)
	v_pk_mul_f32 v[46:47], v[14:15], v[130:131]
	v_pk_mul_f32 v[42:43], v[10:11], v[118:119]
	v_pk_mul_f32 v[38:39], v[6:7], v[114:115]
	v_pk_mul_f32 v[34:35], v[2:3], v[110:111]
	v_pk_mul_f32 v[44:45], v[12:13], v[128:129]
	v_pk_mul_f32 v[40:41], v[8:9], v[116:117]
	v_pk_mul_f32 v[36:37], v[4:5], v[112:113]
	v_pk_mul_f32 v[32:33], v[0:1], v[108:109]
	s_waitcnt lgkmcnt(0)
	v_pk_mul_f32 v[62:63], v[30:31], v[138:139]
	v_pk_mul_f32 v[58:59], v[26:27], v[134:135]
	v_pk_mul_f32 v[54:55], v[22:23], v[126:127]
	v_pk_mul_f32 v[50:51], v[18:19], v[122:123]
	v_pk_mul_f32 v[60:61], v[28:29], v[136:137]
	v_pk_mul_f32 v[56:57], v[24:25], v[132:133]
	v_pk_mul_f32 v[52:53], v[20:21], v[124:125]
	s_and_b64 vcc, exec, s[76:77]
	v_pk_mul_f32 v[48:49], v[16:17], v[120:121]
	s_cbranch_vccnz .LBB0_1061
	v_pk_mul_f32 v[22:23], v[28:29], v[136:137]
	v_pk_mul_f32 v[28:29], v[8:9], v[116:117]
	v_pk_mul_f32 v[2:3], v[4:5], v[112:113]
	v_pk_mul_f32 v[0:1], v[0:1], v[108:109]
	ds_read_b128 v[200:203], v236 offset:8704
	ds_read_b128 v[204:207], v237
	ds_read_b128 v[208:211], v237 offset:32
	ds_read_b128 v[212:215], v238 offset:8704
	ds_read_b128 v[216:219], v239 offset:8704
	ds_read_b128 v[194:197], v237 offset:64
	v_pk_mul_f32 v[26:27], v[12:13], v[128:129]
	v_pk_mul_f32 v[30:31], v[16:17], v[120:121]
	s_waitcnt lgkmcnt(4)
	v_mfma_f32_32x32x16_bf16 v[4:19], v[200:203], v[204:207], 0
	ds_read_b128 v[200:203], v240 offset:8704
	ds_read_b128 v[204:207], v237 offset:96
	v_readlane_b32 s16, v254, 63
	v_readlane_b32 s17, v255, 0
	v_cvt_pk_bf16_f32 v0, v0, v1
	v_cvt_pk_bf16_f32 v1, v34, v35
	v_cvt_pk_bf16_f32 v2, v2, v3
	v_cvt_pk_bf16_f32 v3, v38, v39
	v_pk_mul_f32 v[24:25], v[24:25], v[132:133]
	s_waitcnt lgkmcnt(4)
	v_mfma_f32_32x32x16_bf16 v[4:19], v[212:215], v[208:211], v[4:19]
	ds_read_b128 v[208:211], v241 offset:8704
	ds_read_b128 v[212:215], v237 offset:128
	v_mul_f32_e64 v20, v20, v124
	v_mul_f32_e64 v21, v21, v125
	v_cvt_pk_bf16_f32 v116, v30, v31
	v_cvt_pk_bf16_f32 v117, v50, v51
	v_cvt_pk_bf16_f32 v118, v20, v21
	v_cvt_pk_bf16_f32 v119, v54, v55
	v_cvt_pk_bf16_f32 v28, v28, v29
	s_waitcnt lgkmcnt(4)
	v_mfma_f32_32x32x16_bf16 v[4:19], v[216:219], v[194:197], v[4:19]
	ds_read_b128 v[216:219], v242 offset:8704
	ds_read_b128 v[194:197], v237 offset:160
	v_cvt_pk_bf16_f32 v29, v42, v43
	v_cvt_pk_bf16_f32 v30, v26, v27
	v_cvt_pk_bf16_f32 v31, v46, v47
	v_cvt_pk_bf16_f32 v20, v24, v25
	v_cvt_pk_bf16_f32 v21, v58, v59
	v_cvt_pk_bf16_f32 v22, v22, v23
	s_waitcnt lgkmcnt(4)
	v_mfma_f32_32x32x16_bf16 v[4:19], v[200:203], v[204:207], v[4:19]
	ds_read_b128 v[200:203], v243 offset:8704
	ds_read_b128 v[204:207], v237 offset:192
	v_cvt_pk_bf16_f32 v23, v62, v63
	s_waitcnt lgkmcnt(4)
	v_mfma_f32_32x32x16_bf16 v[4:19], v[208:211], v[212:215], v[4:19]
	ds_read_b128 v[208:211], v244 offset:8704
	ds_read_b128 v[212:215], v237 offset:224
	s_waitcnt lgkmcnt(4)
	v_mfma_f32_32x32x16_bf16 v[4:19], v[216:219], v[194:197], v[4:19]
	s_waitcnt lgkmcnt(2)
	v_mfma_f32_32x32x16_bf16 v[4:19], v[200:203], v[204:207], v[4:19]
	s_waitcnt lgkmcnt(0)
	v_mfma_f32_32x32x16_bf16 v[4:19], v[208:211], v[212:215], v[4:19]
	s_nop 11
	v_cndmask_b32_e64 v64, v4, 0, s[16:17]
	v_readlane_b32 s16, v255, 1
	v_readlane_b32 s17, v255, 2
	v_cndmask_b32_e64 v64, v64, v4, s[40:41]
	v_cndmask_b32_e64 v120, 0, v5, s[40:41]
	v_cndmask_b32_e64 v121, v6, 0, s[16:17]
	v_readlane_b32 s16, v255, 3
	v_readlane_b32 s17, v255, 4
	v_cndmask_b32_e64 v123, v8, 0, s[48:49]
	v_cndmask_b32_e64 v124, v9, 0, s[52:53]
	v_cndmask_b32_e64 v122, v7, 0, s[16:17]
	v_readlane_b32 s16, v255, 5
	ds_read2_b64 v[4:7], v175 offset1:2
	ds_read2_b64 v[108:111], v175 offset0:4 offset1:6
	v_readlane_b32 s17, v255, 6
	ds_read2_b64 v[112:115], v175 offset0:8 offset1:10
	v_cndmask_b32_e64 v125, v10, 0, s[44:45]
	v_cndmask_b32_e64 v128, v13, 0, s[16:17]
	v_readlane_b32 s16, v255, 7
	v_readlane_b32 s17, v255, 8
	v_cndmask_b32_e64 v126, v11, 0, s[36:37]
	v_cndmask_b32_e64 v127, v12, 0, s[42:43]
	v_cndmask_b32_e64 v129, v14, 0, s[16:17]
	v_cndmask_b32_e64 v130, v15, 0, s[60:61]
	v_cndmask_b32_e64 v131, v16, 0, s[62:63]
	v_cndmask_b32_e64 v132, v17, 0, s[64:65]
	s_waitcnt lgkmcnt(2)
	v_mfma_f32_32x32x16_bf16 v[2:17], v[4:7], v[0:3], 0
	v_cndmask_b32_e64 v18, v18, 0, s[66:67]
	v_cndmask_b32_e64 v0, v19, 0, s[68:69]
	v_cvt_pk_bf16_f32 v1, v64, v120
	v_cvt_pk_bf16_f32 v19, v121, v122
	v_cvt_pk_bf16_f32 v24, v131, v132
	v_cvt_pk_bf16_f32 v0, v18, v0
	s_waitcnt lgkmcnt(0)
	v_mfma_f32_32x32x16_bf16 v[2:17], v[112:115], v[116:119], v[2:17]
	v_mfma_f32_32x32x16_bf16 v[2:17], v[108:111], v[28:31], v[2:17]
	ds_read2_b64 v[26:29], v175 offset0:12 offset1:14
	s_waitcnt lgkmcnt(0)
	v_mfma_f32_32x32x16_bf16 v[2:17], v[26:29], v[20:23], v[2:17]
	v_cvt_pk_bf16_f32 v20, v123, v124
	v_cvt_pk_bf16_f32 v21, v125, v126
	v_cvt_pk_bf16_f32 v22, v127, v128
	v_cvt_pk_bf16_f32 v23, v129, v130
	v_cndmask_b32_e64 v21, v0, v21, s[70:71]
	v_cndmask_b32_e64 v20, v24, v20, s[70:71]
	v_cndmask_b32_e64 v19, v23, v19, s[70:71]
	v_cndmask_b32_e64 v18, v22, v1, s[70:71]
	ds_read_b64_tr_b16 v[22:23], v156
	ds_read_b64_tr_b16 v[24:25], v157
	s_waitcnt lgkmcnt(0)
	s_nop 1
	v_mfma_f32_32x32x16_bf16 v[2:17], v[18:21], v[22:25], v[2:17]
	s_and_saveexec_b64 s[20:21], s[72:73]
	s_cbranch_execz .LBB0_1060
	v_add_u32_e32 v0, 0x8000, v231
	s_nop 8
	ds_write2_b32 v0, v2, v3 offset0:128 offset1:160
	ds_write2_b32 v0, v4, v5 offset0:192 offset1:224
	v_add_u32_e32 v0, 0x8400, v231
	ds_write2_b32 v0, v6, v7 offset0:128 offset1:160
	ds_write2_b32 v0, v8, v9 offset0:192 offset1:224
	v_add_u32_e32 v0, 0x8800, v231
	ds_write2_b32 v0, v10, v11 offset0:128 offset1:160
	ds_write2_b32 v0, v12, v13 offset0:192 offset1:224
	v_add_u32_e32 v0, 0x8c00, v231
	ds_write2_b32 v0, v14, v15 offset0:128 offset1:160
	ds_write2_b32 v0, v16, v17 offset0:192 offset1:224

.LBB0_1073:
	ds_read_b128 v[108:111], v172 offset:32768
	ds_read_b128 v[112:115], v172 offset:32800
	ds_read_b128 v[116:119], v172 offset:32832
	ds_read_b128 v[128:131], v172 offset:32864
	ds_read_b128 v[120:123], v172 offset:32896
	ds_read_b128 v[124:127], v172 offset:32928
	ds_read_b128 v[132:135], v172 offset:32960
	ds_read_b128 v[136:139], v172 offset:32992
	s_waitcnt lgkmcnt(4)
	v_pk_mul_f32 v[14:15], v[46:47], v[130:131]
	v_pk_mul_f32 v[10:11], v[42:43], v[118:119]
	v_pk_mul_f32 v[6:7], v[38:39], v[114:115]
	v_pk_mul_f32 v[2:3], v[34:35], v[110:111]
	v_pk_mul_f32 v[12:13], v[44:45], v[128:129]
	v_pk_mul_f32 v[8:9], v[40:41], v[116:117]
	v_pk_mul_f32 v[4:5], v[36:37], v[112:113]
	v_pk_mul_f32 v[0:1], v[32:33], v[108:109]
	s_waitcnt lgkmcnt(0)
	v_pk_mul_f32 v[30:31], v[62:63], v[138:139]
	v_pk_mul_f32 v[26:27], v[58:59], v[134:135]
	v_pk_mul_f32 v[22:23], v[54:55], v[126:127]
	v_pk_mul_f32 v[18:19], v[50:51], v[122:123]
	v_pk_mul_f32 v[28:29], v[60:61], v[136:137]
	v_pk_mul_f32 v[24:25], v[56:57], v[132:133]
	v_pk_mul_f32 v[20:21], v[52:53], v[124:125]
	s_and_b64 vcc, exec, s[76:77]
	v_pk_mul_f32 v[16:17], v[48:49], v[120:121]
	s_cbranch_vccnz .LBB0_1077
	v_pk_mul_f32 v[54:55], v[60:61], v[136:137]
	v_pk_mul_f32 v[60:61], v[40:41], v[116:117]
	v_pk_mul_f32 v[34:35], v[36:37], v[112:113]
	v_pk_mul_f32 v[32:33], v[32:33], v[108:109]
	ds_read_b128 v[200:203], v236 offset:8704
	ds_read_b128 v[204:207], v237
	ds_read_b128 v[208:211], v237 offset:32
	ds_read_b128 v[212:215], v238 offset:8704
	ds_read_b128 v[216:219], v239 offset:8704
	ds_read_b128 v[194:197], v237 offset:64
	v_pk_mul_f32 v[58:59], v[44:45], v[128:129]
	v_pk_mul_f32 v[62:63], v[48:49], v[120:121]
	s_waitcnt lgkmcnt(4)
	v_mfma_f32_32x32x16_bf16 v[36:51], v[200:203], v[204:207], 0
	ds_read_b128 v[200:203], v240 offset:8704
	ds_read_b128 v[204:207], v237 offset:96
	v_readlane_b32 s16, v254, 63
	v_readlane_b32 s17, v255, 0
	v_cvt_pk_bf16_f32 v32, v32, v33
	v_cvt_pk_bf16_f32 v33, v2, v3
	v_cvt_pk_bf16_f32 v34, v34, v35
	v_cvt_pk_bf16_f32 v35, v6, v7
	v_pk_mul_f32 v[56:57], v[56:57], v[132:133]
	s_waitcnt lgkmcnt(4)
	v_mfma_f32_32x32x16_bf16 v[36:51], v[212:215], v[208:211], v[36:51]
	ds_read_b128 v[208:211], v241 offset:8704
	ds_read_b128 v[212:215], v237 offset:128
	v_mul_f32_e64 v52, v52, v124
	v_mul_f32_e64 v53, v53, v125
	v_cvt_pk_bf16_f32 v116, v62, v63
	v_cvt_pk_bf16_f32 v117, v18, v19
	v_cvt_pk_bf16_f32 v118, v52, v53
	v_cvt_pk_bf16_f32 v119, v22, v23
	v_cvt_pk_bf16_f32 v60, v60, v61
	s_waitcnt lgkmcnt(4)
	v_mfma_f32_32x32x16_bf16 v[36:51], v[216:219], v[194:197], v[36:51]
	ds_read_b128 v[216:219], v242 offset:8704
	ds_read_b128 v[194:197], v237 offset:160
	v_cvt_pk_bf16_f32 v61, v10, v11
	v_cvt_pk_bf16_f32 v62, v58, v59
	v_cvt_pk_bf16_f32 v63, v14, v15
	v_cvt_pk_bf16_f32 v52, v56, v57
	v_cvt_pk_bf16_f32 v53, v26, v27
	v_cvt_pk_bf16_f32 v54, v54, v55
	s_waitcnt lgkmcnt(4)
	v_mfma_f32_32x32x16_bf16 v[36:51], v[200:203], v[204:207], v[36:51]
	ds_read_b128 v[200:203], v243 offset:8704
	ds_read_b128 v[204:207], v237 offset:192
	v_cvt_pk_bf16_f32 v55, v30, v31
	s_waitcnt lgkmcnt(4)
	v_mfma_f32_32x32x16_bf16 v[36:51], v[208:211], v[212:215], v[36:51]
	ds_read_b128 v[208:211], v244 offset:8704
	ds_read_b128 v[212:215], v237 offset:224
	s_waitcnt lgkmcnt(4)
	v_mfma_f32_32x32x16_bf16 v[36:51], v[216:219], v[194:197], v[36:51]
	s_waitcnt lgkmcnt(2)
	v_mfma_f32_32x32x16_bf16 v[36:51], v[200:203], v[204:207], v[36:51]
	s_waitcnt lgkmcnt(0)
	v_mfma_f32_32x32x16_bf16 v[36:51], v[208:211], v[212:215], v[36:51]
	s_nop 11
	v_cndmask_b32_e64 v108, v36, 0, s[16:17]
	v_readlane_b32 s16, v255, 1
	v_readlane_b32 s17, v255, 2
	v_cndmask_b32_e64 v120, v108, v36, s[40:41]
	v_cndmask_b32_e64 v121, 0, v37, s[40:41]
	v_cndmask_b32_e64 v122, v38, 0, s[16:17]
	v_readlane_b32 s16, v255, 3
	v_readlane_b32 s17, v255, 4
	v_cndmask_b32_e64 v124, v40, 0, s[48:49]
	v_cndmask_b32_e64 v125, v41, 0, s[52:53]
	v_cndmask_b32_e64 v123, v39, 0, s[16:17]
	v_readlane_b32 s16, v255, 5
	ds_read2_b64 v[36:39], v175 offset1:2
	ds_read2_b64 v[108:111], v175 offset0:4 offset1:6
	v_readlane_b32 s17, v255, 6
	ds_read2_b64 v[112:115], v175 offset0:8 offset1:10
	v_cndmask_b32_e64 v126, v42, 0, s[44:45]
	v_cndmask_b32_e64 v129, v45, 0, s[16:17]
	v_readlane_b32 s16, v255, 7
	v_readlane_b32 s17, v255, 8
	v_cndmask_b32_e64 v127, v43, 0, s[36:37]
	v_cndmask_b32_e64 v128, v44, 0, s[42:43]
	v_cndmask_b32_e64 v130, v46, 0, s[16:17]
	v_cndmask_b32_e64 v131, v47, 0, s[60:61]
	v_cndmask_b32_e64 v132, v48, 0, s[62:63]
	v_cndmask_b32_e64 v133, v49, 0, s[64:65]
	s_waitcnt lgkmcnt(2)
	v_mfma_f32_32x32x16_bf16 v[34:49], v[36:39], v[32:35], 0
	v_cndmask_b32_e64 v50, v50, 0, s[66:67]
	v_cndmask_b32_e64 v32, v51, 0, s[68:69]
	v_cvt_pk_bf16_f32 v33, v120, v121
	v_cvt_pk_bf16_f32 v51, v122, v123
	v_cvt_pk_bf16_f32 v56, v132, v133
	v_cvt_pk_bf16_f32 v32, v50, v32
	s_waitcnt lgkmcnt(0)
	v_mfma_f32_32x32x16_bf16 v[34:49], v[112:115], v[116:119], v[34:49]
	v_mfma_f32_32x32x16_bf16 v[34:49], v[108:111], v[60:63], v[34:49]
	ds_read2_b64 v[58:61], v175 offset0:12 offset1:14
	s_waitcnt lgkmcnt(0)
	v_mfma_f32_32x32x16_bf16 v[34:49], v[58:61], v[52:55], v[34:49]
	v_cvt_pk_bf16_f32 v52, v124, v125
	v_cvt_pk_bf16_f32 v53, v126, v127
	v_cvt_pk_bf16_f32 v54, v128, v129
	v_cvt_pk_bf16_f32 v55, v130, v131
	v_cndmask_b32_e64 v53, v32, v53, s[70:71]
	v_cndmask_b32_e64 v52, v56, v52, s[70:71]
	v_cndmask_b32_e64 v51, v55, v51, s[70:71]
	v_cndmask_b32_e64 v50, v54, v33, s[70:71]
	ds_read_b64_tr_b16 v[54:55], v156
	ds_read_b64_tr_b16 v[56:57], v157
	s_waitcnt lgkmcnt(0)
	s_nop 1
	v_mfma_f32_32x32x16_bf16 v[34:49], v[50:53], v[54:57], v[34:49]
	s_and_saveexec_b64 s[20:21], s[72:73]
	s_cbranch_execz .LBB0_1076
	v_add_u32_e32 v32, 0x8000, v231
	s_nop 8
	ds_write2_b32 v32, v34, v35 offset0:128 offset1:160
	ds_write2_b32 v32, v36, v37 offset0:192 offset1:224
	v_add_u32_e32 v32, 0x8400, v231
	ds_write2_b32 v32, v38, v39 offset0:128 offset1:160
	ds_write2_b32 v32, v40, v41 offset0:192 offset1:224
	v_add_u32_e32 v32, 0x8800, v231
	ds_write2_b32 v32, v42, v43 offset0:128 offset1:160
	ds_write2_b32 v32, v44, v45 offset0:192 offset1:224
	v_add_u32_e32 v32, 0x8c00, v231
	ds_write2_b32 v32, v46, v47 offset0:128 offset1:160
	ds_write2_b32 v32, v48, v49 offset0:192 offset1:224

.LBB0_1160:
	ds_read_b128 v[32:35], v139 offset:32768
	ds_read_b128 v[36:39], v139 offset:32800
	ds_read_b128 v[40:43], v139 offset:32896
	s_waitcnt lgkmcnt(2)
	v_pk_mul_f32 v[0:1], v[0:1], v[32:33]
	v_pk_mul_f32 v[2:3], v[2:3], v[34:35]
	ds_read_b128 v[32:35], v139 offset:32928
	s_waitcnt lgkmcnt(2)
	v_pk_mul_f32 v[4:5], v[4:5], v[36:37]
	v_pk_mul_f32 v[6:7], v[6:7], v[38:39]
	ds_read_b128 v[36:39], v139 offset:32960
	s_waitcnt lgkmcnt(1)
	v_pk_mul_f32 v[20:21], v[20:21], v[32:33]
	v_pk_mul_f32 v[22:23], v[22:23], v[34:35]
	ds_read_b128 v[32:35], v139 offset:32832
	v_pk_mul_f32 v[16:17], v[16:17], v[40:41]
	v_pk_mul_f32 v[18:19], v[18:19], v[42:43]
	s_waitcnt lgkmcnt(0)
	v_pk_mul_f32 v[8:9], v[8:9], v[32:33]
	v_pk_mul_f32 v[10:11], v[10:11], v[34:35]
	ds_read_b128 v[32:35], v139 offset:32864
	v_pk_mul_f32 v[24:25], v[24:25], v[36:37]
	v_pk_mul_f32 v[26:27], v[26:27], v[38:39]
	ds_read_b128 v[36:39], v139 offset:32992
	s_waitcnt lgkmcnt(1)
	v_pk_mul_f32 v[12:13], v[12:13], v[32:33]
	v_pk_mul_f32 v[14:15], v[14:15], v[34:35]
	s_waitcnt lgkmcnt(0)
	v_pk_mul_f32 v[28:29], v[28:29], v[36:37]
	v_pk_mul_f32 v[30:31], v[30:31], v[38:39]
	ds_read_b128 v[200:203], v148 offset:8704
	ds_read_b128 v[204:207], v149
	ds_read_b128 v[208:211], v149 offset:32
	ds_read_b128 v[212:215], v150 offset:8704
	ds_read_b128 v[216:219], v151 offset:8704
	ds_read_b128 v[194:197], v149 offset:64
	s_waitcnt lgkmcnt(4)
	v_mfma_f32_32x32x16_bf16 v[32:47], v[200:203], v[204:207], 0
	ds_read_b128 v[200:203], v152 offset:8704
	ds_read_b128 v[204:207], v149 offset:96
	s_waitcnt lgkmcnt(4)
	v_mfma_f32_32x32x16_bf16 v[32:47], v[212:215], v[208:211], v[32:47]
	ds_read_b128 v[208:211], v153 offset:8704
	ds_read_b128 v[212:215], v149 offset:128
	s_waitcnt lgkmcnt(4)
	v_mfma_f32_32x32x16_bf16 v[32:47], v[216:219], v[194:197], v[32:47]
	ds_read_b128 v[216:219], v154 offset:8704
	ds_read_b128 v[194:197], v149 offset:160
	s_waitcnt lgkmcnt(4)
	v_mfma_f32_32x32x16_bf16 v[32:47], v[200:203], v[204:207], v[32:47]
	ds_read_b128 v[200:203], v155 offset:8704
	ds_read_b128 v[204:207], v149 offset:192
	s_waitcnt lgkmcnt(4)
	v_mfma_f32_32x32x16_bf16 v[32:47], v[208:211], v[212:215], v[32:47]
	ds_read_b128 v[208:211], v156 offset:8704
	ds_read_b128 v[212:215], v149 offset:224
	s_waitcnt lgkmcnt(4)
	v_mfma_f32_32x32x16_bf16 v[32:47], v[216:219], v[194:197], v[32:47]
	s_waitcnt lgkmcnt(2)
	v_mfma_f32_32x32x16_bf16 v[32:47], v[200:203], v[204:207], v[32:47]
	s_waitcnt lgkmcnt(0)
	v_mfma_f32_32x32x16_bf16 v[32:47], v[208:211], v[212:215], v[32:47]
	s_nop 11
	v_cndmask_b32_e64 v48, v32, 0, s[36:37]
	v_cndmask_b32_e64 v64, v48, v32, s[40:41]
	v_cndmask_b32_e64 v160, 0, v33, s[40:41]
	v_cndmask_b32_e64 v161, v34, 0, s[42:43]
	v_cndmask_b32_e64 v162, v35, 0, s[44:45]
	v_cndmask_b32_e64 v163, v36, 0, s[46:47]
	v_cndmask_b32_e64 v164, v37, 0, s[48:49]
	v_cndmask_b32_e64 v165, v38, 0, s[50:51]
	v_cndmask_b32_e64 v166, v39, 0, s[52:53]
	ds_read2_b64 v[32:35], v142 offset1:2
	ds_read2_b64 v[36:39], v142 offset0:4 offset1:6
	v_cndmask_b32_e64 v167, v40, 0, s[54:55]
	v_cndmask_b32_e64 v168, v41, 0, s[56:57]
	v_cndmask_b32_e64 v169, v42, 0, s[58:59]
	v_cndmask_b32_e64 v170, v43, 0, s[60:61]
	v_cvt_pk_bf16_f32 v40, v0, v1
	v_cvt_pk_bf16_f32 v41, v2, v3
	v_cvt_pk_bf16_f32 v42, v4, v5
	v_cvt_pk_bf16_f32 v43, v6, v7
	v_cndmask_b32_e64 v44, v44, 0, s[62:63]
	v_cndmask_b32_e64 v45, v45, 0, s[64:65]
	s_waitcnt lgkmcnt(1)
	v_mfma_f32_32x32x16_bf16 v[48:63], v[32:35], v[40:43], 0
	ds_read2_b64 v[32:35], v142 offset0:8 offset1:10
	v_cvt_pk_bf16_f32 v40, v16, v17
	v_cvt_pk_bf16_f32 v41, v18, v19
	v_cvt_pk_bf16_f32 v42, v20, v21
	v_cvt_pk_bf16_f32 v43, v22, v23
	v_cndmask_b32_e64 v46, v46, 0, s[66:67]
	s_waitcnt lgkmcnt(0)
	v_mfma_f32_32x32x16_bf16 v[48:63], v[32:35], v[40:43], v[48:63]
	v_cvt_pk_bf16_f32 v32, v8, v9
	v_cvt_pk_bf16_f32 v33, v10, v11
	v_cvt_pk_bf16_f32 v34, v12, v13
	v_cvt_pk_bf16_f32 v35, v14, v15
	s_nop 1
	v_mfma_f32_32x32x16_bf16 v[48:63], v[36:39], v[32:35], v[48:63]
	ds_read2_b64 v[32:35], v142 offset0:12 offset1:14
	v_cvt_pk_bf16_f32 v36, v24, v25
	v_cvt_pk_bf16_f32 v37, v26, v27
	v_cvt_pk_bf16_f32 v38, v28, v29
	v_cvt_pk_bf16_f32 v39, v30, v31
	s_waitcnt lgkmcnt(0)
	s_nop 0
	v_mfma_f32_32x32x16_bf16 v[48:63], v[32:35], v[36:39], v[48:63]
	v_cndmask_b32_e64 v32, v47, 0, s[68:69]
	v_cvt_pk_bf16_f32 v36, v64, v160
	v_cvt_pk_bf16_f32 v33, v161, v162
	v_cvt_pk_bf16_f32 v34, v163, v164
	v_cvt_pk_bf16_f32 v35, v165, v166
	v_cvt_pk_bf16_f32 v37, v167, v168
	v_cvt_pk_bf16_f32 v38, v169, v170
	v_cvt_pk_bf16_f32 v39, v44, v45
	v_cvt_pk_bf16_f32 v32, v46, v32
	v_cndmask_b32_e64 v35, v32, v35, s[70:71]
	v_cndmask_b32_e64 v34, v39, v34, s[70:71]
	v_cndmask_b32_e64 v33, v38, v33, s[70:71]
	v_cndmask_b32_e64 v32, v37, v36, s[70:71]
	ds_read_b64_tr_b16 v[36:37], v124
	ds_read_b64_tr_b16 v[38:39], v125
	s_waitcnt lgkmcnt(0)
	v_add_u32_e32 v166, 0x8000, v143
	v_add_u32_e32 v165, 0x8400, v143
	v_mfma_f32_32x32x16_bf16 v[48:63], v[32:35], v[36:39], v[48:63]
	v_add_u32_e32 v164, 0x8800, v143
	v_add_u32_e32 v163, 0x8c00, v143
	s_and_saveexec_b64 s[18:19], s[72:73]
	s_cbranch_execz .LBB0_1162
	s_nop 7
	ds_write2_b32 v166, v48, v49 offset0:128 offset1:160
	ds_write2_b32 v166, v50, v51 offset0:192 offset1:224
	ds_write2_b32 v165, v52, v53 offset0:128 offset1:160
	ds_write2_b32 v165, v54, v55 offset0:192 offset1:224
	ds_write2_b32 v164, v56, v57 offset0:128 offset1:160
	ds_write2_b32 v164, v58, v59 offset0:192 offset1:224
	ds_write2_b32 v163, v60, v61 offset0:128 offset1:160
	ds_write2_b32 v163, v62, v63 offset0:192 offset1:224

.LBB0_1170:
	ds_read_b128 v[32:35], v139 offset:32768
	ds_read_b128 v[36:39], v139 offset:32800
	ds_read_b128 v[40:43], v139 offset:32896
	s_waitcnt lgkmcnt(2)
	v_pk_mul_f32 v[0:1], v[0:1], v[32:33]
	v_pk_mul_f32 v[2:3], v[2:3], v[34:35]
	ds_read_b128 v[32:35], v139 offset:32928
	s_waitcnt lgkmcnt(2)
	v_pk_mul_f32 v[4:5], v[4:5], v[36:37]
	v_pk_mul_f32 v[6:7], v[6:7], v[38:39]
	ds_read_b128 v[36:39], v139 offset:32960
	s_waitcnt lgkmcnt(1)
	v_pk_mul_f32 v[20:21], v[20:21], v[32:33]
	v_pk_mul_f32 v[22:23], v[22:23], v[34:35]
	ds_read_b128 v[32:35], v139 offset:32832
	v_pk_mul_f32 v[16:17], v[16:17], v[40:41]
	v_pk_mul_f32 v[18:19], v[18:19], v[42:43]
	s_waitcnt lgkmcnt(0)
	v_pk_mul_f32 v[8:9], v[8:9], v[32:33]
	v_pk_mul_f32 v[10:11], v[10:11], v[34:35]
	ds_read_b128 v[32:35], v139 offset:32864
	v_pk_mul_f32 v[24:25], v[24:25], v[36:37]
	v_pk_mul_f32 v[26:27], v[26:27], v[38:39]
	ds_read_b128 v[36:39], v139 offset:32992
	s_waitcnt lgkmcnt(1)
	v_pk_mul_f32 v[12:13], v[12:13], v[32:33]
	v_pk_mul_f32 v[14:15], v[14:15], v[34:35]
	s_waitcnt lgkmcnt(0)
	v_pk_mul_f32 v[28:29], v[28:29], v[36:37]
	v_pk_mul_f32 v[30:31], v[30:31], v[38:39]
	ds_read_b128 v[200:203], v148 offset:8704
	ds_read_b128 v[204:207], v149
	ds_read_b128 v[208:211], v149 offset:32
	ds_read_b128 v[212:215], v150 offset:8704
	ds_read_b128 v[216:219], v151 offset:8704
	ds_read_b128 v[194:197], v149 offset:64
	s_waitcnt lgkmcnt(4)
	v_mfma_f32_32x32x16_bf16 v[32:47], v[200:203], v[204:207], 0
	ds_read_b128 v[200:203], v152 offset:8704
	ds_read_b128 v[204:207], v149 offset:96
	s_waitcnt lgkmcnt(4)
	v_mfma_f32_32x32x16_bf16 v[32:47], v[212:215], v[208:211], v[32:47]
	ds_read_b128 v[208:211], v153 offset:8704
	ds_read_b128 v[212:215], v149 offset:128
	s_waitcnt lgkmcnt(4)
	v_mfma_f32_32x32x16_bf16 v[32:47], v[216:219], v[194:197], v[32:47]
	ds_read_b128 v[216:219], v154 offset:8704
	ds_read_b128 v[194:197], v149 offset:160
	s_waitcnt lgkmcnt(4)
	v_mfma_f32_32x32x16_bf16 v[32:47], v[200:203], v[204:207], v[32:47]
	ds_read_b128 v[200:203], v155 offset:8704
	ds_read_b128 v[204:207], v149 offset:192
	s_waitcnt lgkmcnt(4)
	v_mfma_f32_32x32x16_bf16 v[32:47], v[208:211], v[212:215], v[32:47]
	ds_read_b128 v[208:211], v156 offset:8704
	ds_read_b128 v[212:215], v149 offset:224
	s_waitcnt lgkmcnt(4)
	v_mfma_f32_32x32x16_bf16 v[32:47], v[216:219], v[194:197], v[32:47]
	s_waitcnt lgkmcnt(2)
	v_mfma_f32_32x32x16_bf16 v[32:47], v[200:203], v[204:207], v[32:47]
	s_waitcnt lgkmcnt(0)
	v_mfma_f32_32x32x16_bf16 v[32:47], v[208:211], v[212:215], v[32:47]
	s_nop 11
	v_cndmask_b32_e64 v48, v32, 0, s[36:37]
	v_cndmask_b32_e64 v167, v48, v32, s[40:41]
	v_cndmask_b32_e64 v168, 0, v33, s[40:41]
	v_cndmask_b32_e64 v169, v34, 0, s[42:43]
	v_cndmask_b32_e64 v170, v35, 0, s[44:45]
	v_cndmask_b32_e64 v171, v36, 0, s[46:47]
	v_cndmask_b32_e64 v172, v37, 0, s[48:49]
	v_cndmask_b32_e64 v173, v38, 0, s[50:51]
	v_cndmask_b32_e64 v174, v39, 0, s[52:53]
	ds_read2_b64 v[32:35], v142 offset1:2
	ds_read2_b64 v[36:39], v142 offset0:4 offset1:6
	v_cndmask_b32_e64 v175, v40, 0, s[54:55]
	v_cndmask_b32_e64 v193, v41, 0, s[56:57]
	v_cndmask_b32_e64 v194, v42, 0, s[58:59]
	v_cndmask_b32_e64 v195, v43, 0, s[60:61]
	v_cvt_pk_bf16_f32 v40, v0, v1
	v_cvt_pk_bf16_f32 v41, v2, v3
	v_cvt_pk_bf16_f32 v42, v4, v5
	v_cvt_pk_bf16_f32 v43, v6, v7
	v_cndmask_b32_e64 v44, v44, 0, s[62:63]
	v_cndmask_b32_e64 v45, v45, 0, s[64:65]
	s_waitcnt lgkmcnt(1)
	v_mfma_f32_32x32x16_bf16 v[48:63], v[32:35], v[40:43], 0
	ds_read2_b64 v[32:35], v142 offset0:8 offset1:10
	v_cvt_pk_bf16_f32 v40, v16, v17
	v_cvt_pk_bf16_f32 v41, v18, v19
	v_cvt_pk_bf16_f32 v42, v20, v21
	v_cvt_pk_bf16_f32 v43, v22, v23
	v_cndmask_b32_e64 v46, v46, 0, s[66:67]
	s_waitcnt lgkmcnt(0)
	v_mfma_f32_32x32x16_bf16 v[48:63], v[32:35], v[40:43], v[48:63]
	v_cvt_pk_bf16_f32 v32, v8, v9
	v_cvt_pk_bf16_f32 v33, v10, v11
	v_cvt_pk_bf16_f32 v34, v12, v13
	v_cvt_pk_bf16_f32 v35, v14, v15
	s_nop 1
	v_mfma_f32_32x32x16_bf16 v[48:63], v[36:39], v[32:35], v[48:63]
	ds_read2_b64 v[32:35], v142 offset0:12 offset1:14
	v_cvt_pk_bf16_f32 v36, v24, v25
	v_cvt_pk_bf16_f32 v37, v26, v27
	v_cvt_pk_bf16_f32 v38, v28, v29
	v_cvt_pk_bf16_f32 v39, v30, v31
	s_waitcnt lgkmcnt(0)
	s_nop 0
	v_mfma_f32_32x32x16_bf16 v[48:63], v[32:35], v[36:39], v[48:63]
	v_cndmask_b32_e64 v32, v47, 0, s[68:69]
	v_cvt_pk_bf16_f32 v36, v167, v168
	v_cvt_pk_bf16_f32 v33, v169, v170
	v_cvt_pk_bf16_f32 v34, v171, v172
	v_cvt_pk_bf16_f32 v35, v173, v174
	v_cvt_pk_bf16_f32 v37, v175, v193
	v_cvt_pk_bf16_f32 v38, v194, v195
	v_cvt_pk_bf16_f32 v39, v44, v45
	v_cvt_pk_bf16_f32 v32, v46, v32
	v_cndmask_b32_e64 v35, v32, v35, s[70:71]
	v_cndmask_b32_e64 v34, v39, v34, s[70:71]
	v_cndmask_b32_e64 v33, v38, v33, s[70:71]
	v_cndmask_b32_e64 v32, v37, v36, s[70:71]
	ds_read_b64_tr_b16 v[36:37], v124
	ds_read_b64_tr_b16 v[38:39], v125
	s_waitcnt lgkmcnt(0)
	s_nop 1
	v_mfma_f32_32x32x16_bf16 v[48:63], v[32:35], v[36:39], v[48:63]
	s_and_saveexec_b64 s[10:11], s[72:73]
	s_cbranch_execz .LBB0_1172
	s_nop 9
	ds_write2_b32 v166, v48, v49 offset0:128 offset1:160
	ds_write2_b32 v166, v50, v51 offset0:192 offset1:224
	ds_write2_b32 v165, v52, v53 offset0:128 offset1:160
	ds_write2_b32 v165, v54, v55 offset0:192 offset1:224
	ds_write2_b32 v164, v56, v57 offset0:128 offset1:160
	ds_write2_b32 v164, v58, v59 offset0:192 offset1:224
	ds_write2_b32 v163, v60, v61 offset0:128 offset1:160
	ds_write2_b32 v163, v62, v63 offset0:192 offset1:224

.LBB0_1300:
	s_andn2_b64 vcc, exec, s[8:9]
	s_cbranch_vccnz .LBB0_1297
	s_lshl_b64 s[4:5], s[36:37], 11
	v_lshl_add_u64 v[140:141], v[136:137], 0, s[4:5]
	v_add_co_u32_e32 v142, vcc, 0x10000, v140
	global_load_dwordx4 v[0:3], v[140:141], off
	s_nop 0
	v_addc_co_u32_e32 v143, vcc, 0, v141, vcc
	v_add_co_u32_e32 v144, vcc, 0x20000, v140
	global_load_dwordx4 v[4:7], v[142:143], off
	s_nop 0
	v_addc_co_u32_e32 v145, vcc, 0, v141, vcc
	v_add_co_u32_e32 v146, vcc, 0x30000, v140
	global_load_dwordx4 v[8:11], v[144:145], off
	s_nop 0
	v_addc_co_u32_e32 v147, vcc, 0, v141, vcc
	global_load_dwordx4 v[12:15], v[146:147], off
	global_load_dwordx4 v[16:19], v[138:139], off
	s_mov_b32 s12, 0x10000
	v_add_co_u32_e32 v148, vcc, s12, v138
	s_nop 1
	v_addc_co_u32_e32 v149, vcc, 0, v139, vcc
	v_add_co_u32_e32 v150, vcc, 0x20000, v138
	global_load_dwordx4 v[20:23], v[148:149], off
	s_nop 0
	v_addc_co_u32_e32 v151, vcc, 0, v139, vcc
	global_load_dwordx4 v[24:27], v[150:151], off
	v_add_co_u32_e32 v152, vcc, 0x30000, v138
	s_nop 1
	v_addc_co_u32_e32 v153, vcc, 0, v139, vcc
	global_load_dwordx4 v[28:31], v[152:153], off
	global_load_dwordx4 v[66:69], v[140:141], off offset:128
	global_load_dwordx4 v[70:73], v[142:143], off offset:128
	global_load_dwordx4 v[74:77], v[144:145], off offset:128
	global_load_dwordx4 v[78:81], v[146:147], off offset:128
	global_load_dwordx4 v[82:85], v[138:139], off offset:128
	global_load_dwordx4 v[106:109], v[148:149], off offset:128
	global_load_dwordx4 v[110:113], v[150:151], off offset:128
	global_load_dwordx4 v[122:125], v[152:153], off offset:128
	s_waitcnt vmcnt(63) expcnt(7) lgkmcnt(15)
	s_barrier
	s_waitcnt vmcnt(15)
	ds_write_b128 v132, v[0:3]
	s_waitcnt vmcnt(14)
	ds_write_b128 v132, v[4:7] offset:4608
	s_waitcnt vmcnt(13)
	ds_write_b128 v132, v[8:11] offset:9216
	s_waitcnt vmcnt(12)
	ds_write_b128 v132, v[12:15] offset:13824
	s_waitcnt vmcnt(11)
	ds_write_b128 v132, v[16:19] offset:18432
	s_waitcnt vmcnt(10)
	ds_write_b128 v132, v[20:23] offset:23040
	s_waitcnt vmcnt(9)
	ds_write_b128 v132, v[24:27] offset:27648
	s_waitcnt vmcnt(8)
	ds_write_b128 v132, v[28:31] offset:32256
	global_load_dwordx4 v[86:89], v[140:141], off offset:256
	global_load_dwordx4 v[90:93], v[142:143], off offset:256
	global_load_dwordx4 v[94:97], v[144:145], off offset:256
	global_load_dwordx4 v[98:101], v[146:147], off offset:256
	global_load_dwordx4 v[102:105], v[138:139], off offset:256
	global_load_dwordx4 v[114:117], v[148:149], off offset:256
	global_load_dwordx4 v[118:121], v[150:151], off offset:256
	global_load_dwordx4 v[126:129], v[152:153], off offset:256
	s_waitcnt lgkmcnt(0)
	s_barrier
	s_setprio 1
	ds_read_b128 v[200:203], v134
	ds_read_b128 v[204:207], v156 offset:18432
	ds_read_b128 v[208:211], v156 offset:23040
	ds_read_b128 v[212:215], v134 offset:32
	ds_read_b128 v[232:235], v156 offset:18464
	ds_read_b128 v[236:239], v156 offset:23072
	ds_read_b128 v[240:243], v134 offset:4608
	ds_read_b128 v[244:247], v134 offset:4640
	s_waitcnt lgkmcnt(6)
	v_mfma_f32_32x32x16_bf16 v[48:63], v[200:203], v[204:207], 0
	s_waitcnt lgkmcnt(5)
	v_mfma_f32_32x32x16_bf16 v[32:47], v[200:203], v[208:211], 0
	s_waitcnt vmcnt(15)
	ds_write_b128 v132, v[66:69] offset:36864
	s_waitcnt vmcnt(14)
	ds_write_b128 v132, v[70:73] offset:41472
	ds_read_b128 v[200:203], v134 offset:64
	s_waitcnt lgkmcnt(6)
	v_mfma_f32_32x32x16_bf16 v[48:63], v[212:215], v[232:235], v[48:63]
	s_waitcnt vmcnt(13)
	ds_write_b128 v132, v[74:77] offset:46080
	s_waitcnt lgkmcnt(6)
	v_mfma_f32_32x32x16_bf16 v[32:47], v[212:215], v[236:239], v[32:47]
	s_waitcnt vmcnt(12)
	ds_write_b128 v132, v[78:81] offset:50688
	ds_read_b128 v[212:215], v156 offset:18496
	s_waitcnt lgkmcnt(7)
	v_mfma_f32_32x32x16_bf16 v[16:31], v[240:243], v[204:207], 0
	s_waitcnt vmcnt(11)
	ds_write_b128 v132, v[82:85] offset:55296
	ds_read_b128 v[204:207], v156 offset:23104
	v_mfma_f32_32x32x16_bf16 v[0:15], v[240:243], v[208:211], 0
	s_waitcnt vmcnt(10)
	ds_write_b128 v132, v[106:109] offset:59904
	ds_read_b128 v[208:211], v134 offset:4672
	ds_read_b128 v[240:243], v134 offset:96
	s_waitcnt lgkmcnt(11)
	v_mfma_f32_32x32x16_bf16 v[16:31], v[244:247], v[232:235], v[16:31]
	s_waitcnt vmcnt(9)
	ds_write_b128 v132, v[110:113] offset:64512
	ds_read_b128 v[232:235], v156 offset:18528
	v_mfma_f32_32x32x16_bf16 v[0:15], v[244:247], v[236:239], v[0:15]
	s_waitcnt vmcnt(8)
	ds_write_b128 v133, v[122:125] offset:32256
	ds_read_b128 v[236:239], v156 offset:23136
	ds_read_b128 v[244:247], v134 offset:4704
	s_waitcnt lgkmcnt(10)
	v_mfma_f32_32x32x16_bf16 v[48:63], v[200:203], v[212:215], v[48:63]
	global_load_dwordx4 v[66:69], v[140:141], off offset:384
	s_waitcnt lgkmcnt(8)
	v_mfma_f32_32x32x16_bf16 v[32:47], v[200:203], v[204:207], v[32:47]
	global_load_dwordx4 v[70:73], v[142:143], off offset:384
	s_waitcnt lgkmcnt(6)
	v_mfma_f32_32x32x16_bf16 v[16:31], v[208:211], v[212:215], v[16:31]
	global_load_dwordx4 v[74:77], v[144:145], off offset:384
	v_mfma_f32_32x32x16_bf16 v[0:15], v[208:211], v[204:207], v[0:15]
	global_load_dwordx4 v[78:81], v[146:147], off offset:384
	s_waitcnt lgkmcnt(3)
	v_mfma_f32_32x32x16_bf16 v[48:63], v[240:243], v[232:235], v[48:63]
	global_load_dwordx4 v[82:85], v[138:139], off offset:384
	s_waitcnt lgkmcnt(1)
	v_mfma_f32_32x32x16_bf16 v[32:47], v[240:243], v[236:239], v[32:47]
	global_load_dwordx4 v[106:109], v[148:149], off offset:384
	s_waitcnt lgkmcnt(0)
	v_mfma_f32_32x32x16_bf16 v[16:31], v[244:247], v[232:235], v[16:31]
	global_load_dwordx4 v[110:113], v[150:151], off offset:384
	v_mfma_f32_32x32x16_bf16 v[0:15], v[244:247], v[236:239], v[0:15]
	global_load_dwordx4 v[122:125], v[152:153], off offset:384
	s_setprio 0
	s_waitcnt lgkmcnt(0)
	s_barrier
	s_setprio 1
	ds_read_b128 v[200:203], v134 offset:36864
	ds_read_b128 v[204:207], v156 offset:55296
	ds_read_b128 v[208:211], v156 offset:59904
	ds_read_b128 v[212:215], v134 offset:41472
	ds_read_b128 v[232:235], v134 offset:36896
	ds_read_b128 v[236:239], v156 offset:55328
	ds_read_b128 v[240:243], v156 offset:59936
	ds_read_b128 v[244:247], v134 offset:41504
	s_waitcnt lgkmcnt(6)
	v_mfma_f32_32x32x16_bf16 v[48:63], v[200:203], v[204:207], v[48:63]
	s_waitcnt lgkmcnt(5)
	v_mfma_f32_32x32x16_bf16 v[32:47], v[200:203], v[208:211], v[32:47]
	s_waitcnt vmcnt(15)
	ds_write_b128 v132, v[86:89]
	s_waitcnt vmcnt(14)
	ds_write_b128 v132, v[90:93] offset:4608
	ds_read_b128 v[200:203], v134 offset:36928
	s_waitcnt lgkmcnt(7)
	v_mfma_f32_32x32x16_bf16 v[16:31], v[212:215], v[204:207], v[16:31]
	s_waitcnt vmcnt(13)
	ds_write_b128 v132, v[94:97] offset:9216
	ds_read_b128 v[204:207], v156 offset:55360
	v_mfma_f32_32x32x16_bf16 v[0:15], v[212:215], v[208:211], v[0:15]
	s_waitcnt vmcnt(12)
	ds_write_b128 v132, v[98:101] offset:13824
	ds_read_b128 v[208:211], v156 offset:59968
	ds_read_b128 v[212:215], v134 offset:41536
	s_waitcnt lgkmcnt(10)
	v_mfma_f32_32x32x16_bf16 v[48:63], v[232:235], v[236:239], v[48:63]
	s_waitcnt vmcnt(11)
	ds_write_b128 v132, v[102:105] offset:18432
	s_waitcnt lgkmcnt(10)
	v_mfma_f32_32x32x16_bf16 v[32:47], v[232:235], v[240:243], v[32:47]
	s_waitcnt vmcnt(10)
	ds_write_b128 v132, v[114:117] offset:23040
	ds_read_b128 v[232:235], v134 offset:36960
	s_waitcnt lgkmcnt(11)
	v_mfma_f32_32x32x16_bf16 v[16:31], v[244:247], v[236:239], v[16:31]
	s_waitcnt vmcnt(9)
	ds_write_b128 v132, v[118:121] offset:27648
	ds_read_b128 v[236:239], v156 offset:55392
	v_mfma_f32_32x32x16_bf16 v[0:15], v[244:247], v[240:243], v[0:15]
	s_waitcnt vmcnt(8)
	ds_write_b128 v132, v[126:129] offset:32256
	ds_read_b128 v[240:243], v156 offset:60000
	ds_read_b128 v[244:247], v134 offset:41568
	s_waitcnt lgkmcnt(11)
	v_mfma_f32_32x32x16_bf16 v[48:63], v[200:203], v[204:207], v[48:63]
	global_load_dwordx4 v[86:89], v[140:141], off offset:512
	s_waitcnt lgkmcnt(9)
	v_mfma_f32_32x32x16_bf16 v[32:47], v[200:203], v[208:211], v[32:47]
	global_load_dwordx4 v[90:93], v[142:143], off offset:512
	s_waitcnt lgkmcnt(8)
	v_mfma_f32_32x32x16_bf16 v[16:31], v[212:215], v[204:207], v[16:31]
	global_load_dwordx4 v[94:97], v[144:145], off offset:512
	v_mfma_f32_32x32x16_bf16 v[0:15], v[212:215], v[208:211], v[0:15]
	global_load_dwordx4 v[98:101], v[146:147], off offset:512
	s_waitcnt lgkmcnt(3)
	v_mfma_f32_32x32x16_bf16 v[48:63], v[232:235], v[236:239], v[48:63]
	global_load_dwordx4 v[102:105], v[138:139], off offset:512
	s_waitcnt lgkmcnt(1)
	v_mfma_f32_32x32x16_bf16 v[32:47], v[232:235], v[240:243], v[32:47]
	global_load_dwordx4 v[114:117], v[148:149], off offset:512
	s_waitcnt lgkmcnt(0)
	v_mfma_f32_32x32x16_bf16 v[16:31], v[244:247], v[236:239], v[16:31]
	global_load_dwordx4 v[118:121], v[150:151], off offset:512
	v_mfma_f32_32x32x16_bf16 v[0:15], v[244:247], v[240:243], v[0:15]
	global_load_dwordx4 v[126:129], v[152:153], off offset:512
	s_setprio 0
	s_waitcnt lgkmcnt(0)
	s_barrier
	s_setprio 1
	ds_read_b128 v[200:203], v134
	ds_read_b128 v[204:207], v156 offset:18432
	ds_read_b128 v[208:211], v156 offset:23040
	ds_read_b128 v[212:215], v134 offset:4608
	ds_read_b128 v[232:235], v134 offset:32
	ds_read_b128 v[236:239], v156 offset:18464
	ds_read_b128 v[240:243], v156 offset:23072
	ds_read_b128 v[244:247], v134 offset:4640
	s_waitcnt lgkmcnt(6)
	v_mfma_f32_32x32x16_bf16 v[48:63], v[200:203], v[204:207], v[48:63]
	s_waitcnt lgkmcnt(5)
	v_mfma_f32_32x32x16_bf16 v[32:47], v[200:203], v[208:211], v[32:47]
	s_waitcnt vmcnt(15)
	ds_write_b128 v132, v[66:69] offset:36864
	s_waitcnt vmcnt(14)
	ds_write_b128 v132, v[70:73] offset:41472
	ds_read_b128 v[200:203], v134 offset:64
	s_waitcnt lgkmcnt(7)
	v_mfma_f32_32x32x16_bf16 v[16:31], v[212:215], v[204:207], v[16:31]
	s_waitcnt vmcnt(13)
	ds_write_b128 v132, v[74:77] offset:46080
	ds_read_b128 v[204:207], v156 offset:18496
	v_mfma_f32_32x32x16_bf16 v[0:15], v[212:215], v[208:211], v[0:15]
	s_waitcnt vmcnt(12)
	ds_write_b128 v132, v[78:81] offset:50688
	ds_read_b128 v[208:211], v156 offset:23104
	ds_read_b128 v[212:215], v134 offset:4672
	s_waitcnt lgkmcnt(10)
	v_mfma_f32_32x32x16_bf16 v[48:63], v[232:235], v[236:239], v[48:63]
	s_waitcnt vmcnt(11)
	ds_write_b128 v132, v[82:85] offset:55296
	s_waitcnt lgkmcnt(10)
	v_mfma_f32_32x32x16_bf16 v[32:47], v[232:235], v[240:243], v[32:47]
	s_waitcnt vmcnt(10)
	ds_write_b128 v132, v[106:109] offset:59904
	ds_read_b128 v[232:235], v134 offset:96
	s_waitcnt lgkmcnt(11)
	v_mfma_f32_32x32x16_bf16 v[16:31], v[244:247], v[236:239], v[16:31]
	s_waitcnt vmcnt(9)
	ds_write_b128 v132, v[110:113] offset:64512
	ds_read_b128 v[236:239], v156 offset:18528
	v_mfma_f32_32x32x16_bf16 v[0:15], v[244:247], v[240:243], v[0:15]
	s_waitcnt vmcnt(8)
	ds_write_b128 v133, v[122:125] offset:32256
	ds_read_b128 v[240:243], v156 offset:23136
	ds_read_b128 v[244:247], v134 offset:4704
	s_waitcnt lgkmcnt(11)
	v_mfma_f32_32x32x16_bf16 v[48:63], v[200:203], v[204:207], v[48:63]
	global_load_dwordx4 v[66:69], v[140:141], off offset:640
	s_waitcnt lgkmcnt(9)
	v_mfma_f32_32x32x16_bf16 v[32:47], v[200:203], v[208:211], v[32:47]
	global_load_dwordx4 v[70:73], v[142:143], off offset:640
	s_waitcnt lgkmcnt(8)
	v_mfma_f32_32x32x16_bf16 v[16:31], v[212:215], v[204:207], v[16:31]
	global_load_dwordx4 v[74:77], v[144:145], off offset:640
	v_mfma_f32_32x32x16_bf16 v[0:15], v[212:215], v[208:211], v[0:15]
	global_load_dwordx4 v[78:81], v[146:147], off offset:640
	s_waitcnt lgkmcnt(3)
	v_mfma_f32_32x32x16_bf16 v[48:63], v[232:235], v[236:239], v[48:63]
	global_load_dwordx4 v[82:85], v[138:139], off offset:640
	s_waitcnt lgkmcnt(1)
	v_mfma_f32_32x32x16_bf16 v[32:47], v[232:235], v[240:243], v[32:47]
	global_load_dwordx4 v[106:109], v[148:149], off offset:640
	s_waitcnt lgkmcnt(0)
	v_mfma_f32_32x32x16_bf16 v[16:31], v[244:247], v[236:239], v[16:31]
	global_load_dwordx4 v[110:113], v[150:151], off offset:640
	v_mfma_f32_32x32x16_bf16 v[0:15], v[244:247], v[240:243], v[0:15]
	global_load_dwordx4 v[122:125], v[152:153], off offset:640
	s_setprio 0
	s_waitcnt lgkmcnt(0)
	s_barrier
	s_setprio 1
	ds_read_b128 v[200:203], v134 offset:36864
	ds_read_b128 v[204:207], v156 offset:55296
	ds_read_b128 v[208:211], v156 offset:59904
	ds_read_b128 v[212:215], v134 offset:41472
	ds_read_b128 v[232:235], v134 offset:36896
	ds_read_b128 v[236:239], v156 offset:55328
	ds_read_b128 v[240:243], v156 offset:59936
	ds_read_b128 v[244:247], v134 offset:41504
	s_waitcnt lgkmcnt(6)
	v_mfma_f32_32x32x16_bf16 v[48:63], v[200:203], v[204:207], v[48:63]
	s_waitcnt lgkmcnt(5)
	v_mfma_f32_32x32x16_bf16 v[32:47], v[200:203], v[208:211], v[32:47]
	s_waitcnt vmcnt(15)
	ds_write_b128 v132, v[86:89]
	s_waitcnt vmcnt(14)
	ds_write_b128 v132, v[90:93] offset:4608
	ds_read_b128 v[200:203], v134 offset:36928
	s_waitcnt lgkmcnt(7)
	v_mfma_f32_32x32x16_bf16 v[16:31], v[212:215], v[204:207], v[16:31]
	s_waitcnt vmcnt(13)
	ds_write_b128 v132, v[94:97] offset:9216
	ds_read_b128 v[204:207], v156 offset:55360
	v_mfma_f32_32x32x16_bf16 v[0:15], v[212:215], v[208:211], v[0:15]
	s_waitcnt vmcnt(12)
	ds_write_b128 v132, v[98:101] offset:13824
	ds_read_b128 v[208:211], v156 offset:59968
	ds_read_b128 v[212:215], v134 offset:41536
	s_waitcnt lgkmcnt(10)
	v_mfma_f32_32x32x16_bf16 v[48:63], v[232:235], v[236:239], v[48:63]
	s_waitcnt vmcnt(11)
	ds_write_b128 v132, v[102:105] offset:18432
	s_waitcnt lgkmcnt(10)
	v_mfma_f32_32x32x16_bf16 v[32:47], v[232:235], v[240:243], v[32:47]
	s_waitcnt vmcnt(10)
	ds_write_b128 v132, v[114:117] offset:23040
	ds_read_b128 v[232:235], v134 offset:36960
	s_waitcnt lgkmcnt(11)
	v_mfma_f32_32x32x16_bf16 v[16:31], v[244:247], v[236:239], v[16:31]
	s_waitcnt vmcnt(9)
	ds_write_b128 v132, v[118:121] offset:27648
	ds_read_b128 v[236:239], v156 offset:55392
	v_mfma_f32_32x32x16_bf16 v[0:15], v[244:247], v[240:243], v[0:15]
	s_waitcnt vmcnt(8)
	ds_write_b128 v132, v[126:129] offset:32256
	ds_read_b128 v[240:243], v156 offset:60000
	ds_read_b128 v[244:247], v134 offset:41568
	s_waitcnt lgkmcnt(11)
	v_mfma_f32_32x32x16_bf16 v[48:63], v[200:203], v[204:207], v[48:63]
	global_load_dwordx4 v[86:89], v[140:141], off offset:768
	s_waitcnt lgkmcnt(9)
	v_mfma_f32_32x32x16_bf16 v[32:47], v[200:203], v[208:211], v[32:47]
	global_load_dwordx4 v[90:93], v[142:143], off offset:768
	s_waitcnt lgkmcnt(8)
	v_mfma_f32_32x32x16_bf16 v[16:31], v[212:215], v[204:207], v[16:31]
	global_load_dwordx4 v[94:97], v[144:145], off offset:768
	v_mfma_f32_32x32x16_bf16 v[0:15], v[212:215], v[208:211], v[0:15]
	global_load_dwordx4 v[98:101], v[146:147], off offset:768
	s_waitcnt lgkmcnt(3)
	v_mfma_f32_32x32x16_bf16 v[48:63], v[232:235], v[236:239], v[48:63]
	global_load_dwordx4 v[102:105], v[138:139], off offset:768
	s_waitcnt lgkmcnt(1)
	v_mfma_f32_32x32x16_bf16 v[32:47], v[232:235], v[240:243], v[32:47]
	global_load_dwordx4 v[114:117], v[148:149], off offset:768
	s_waitcnt lgkmcnt(0)
	v_mfma_f32_32x32x16_bf16 v[16:31], v[244:247], v[236:239], v[16:31]
	global_load_dwordx4 v[118:121], v[150:151], off offset:768
	v_mfma_f32_32x32x16_bf16 v[0:15], v[244:247], v[240:243], v[0:15]
	global_load_dwordx4 v[126:129], v[152:153], off offset:768
	s_setprio 0
	s_waitcnt lgkmcnt(0)
	s_barrier
	s_setprio 1
	ds_read_b128 v[200:203], v134
	ds_read_b128 v[204:207], v156 offset:18432
	ds_read_b128 v[208:211], v156 offset:23040
	ds_read_b128 v[212:215], v134 offset:4608
	ds_read_b128 v[232:235], v134 offset:32
	ds_read_b128 v[236:239], v156 offset:18464
	ds_read_b128 v[240:243], v156 offset:23072
	ds_read_b128 v[244:247], v134 offset:4640
	s_waitcnt lgkmcnt(6)
	v_mfma_f32_32x32x16_bf16 v[48:63], v[200:203], v[204:207], v[48:63]
	s_waitcnt lgkmcnt(5)
	v_mfma_f32_32x32x16_bf16 v[32:47], v[200:203], v[208:211], v[32:47]
	s_waitcnt vmcnt(15)
	ds_write_b128 v132, v[66:69] offset:36864
	s_waitcnt vmcnt(14)
	ds_write_b128 v132, v[70:73] offset:41472
	ds_read_b128 v[200:203], v134 offset:64
	s_waitcnt lgkmcnt(7)
	v_mfma_f32_32x32x16_bf16 v[16:31], v[212:215], v[204:207], v[16:31]
	s_waitcnt vmcnt(13)
	ds_write_b128 v132, v[74:77] offset:46080
	ds_read_b128 v[204:207], v156 offset:18496
	v_mfma_f32_32x32x16_bf16 v[0:15], v[212:215], v[208:211], v[0:15]
	s_waitcnt vmcnt(12)
	ds_write_b128 v132, v[78:81] offset:50688
	ds_read_b128 v[208:211], v156 offset:23104
	ds_read_b128 v[212:215], v134 offset:4672
	s_waitcnt lgkmcnt(10)
	v_mfma_f32_32x32x16_bf16 v[48:63], v[232:235], v[236:239], v[48:63]
	s_waitcnt vmcnt(11)
	ds_write_b128 v132, v[82:85] offset:55296
	s_waitcnt lgkmcnt(10)
	v_mfma_f32_32x32x16_bf16 v[32:47], v[232:235], v[240:243], v[32:47]
	s_waitcnt vmcnt(10)
	ds_write_b128 v132, v[106:109] offset:59904
	ds_read_b128 v[232:235], v134 offset:96
	s_waitcnt lgkmcnt(11)
	v_mfma_f32_32x32x16_bf16 v[16:31], v[244:247], v[236:239], v[16:31]
	s_waitcnt vmcnt(9)
	ds_write_b128 v132, v[110:113] offset:64512
	ds_read_b128 v[236:239], v156 offset:18528
	v_mfma_f32_32x32x16_bf16 v[0:15], v[244:247], v[240:243], v[0:15]
	s_waitcnt vmcnt(8)
	ds_write_b128 v133, v[122:125] offset:32256
	ds_read_b128 v[240:243], v156 offset:23136
	ds_read_b128 v[244:247], v134 offset:4704
	s_waitcnt lgkmcnt(11)
	v_mfma_f32_32x32x16_bf16 v[48:63], v[200:203], v[204:207], v[48:63]
	global_load_dwordx4 v[66:69], v[140:141], off offset:896
	s_waitcnt lgkmcnt(9)
	v_mfma_f32_32x32x16_bf16 v[32:47], v[200:203], v[208:211], v[32:47]
	global_load_dwordx4 v[70:73], v[142:143], off offset:896
	s_waitcnt lgkmcnt(8)
	v_mfma_f32_32x32x16_bf16 v[16:31], v[212:215], v[204:207], v[16:31]
	global_load_dwordx4 v[74:77], v[144:145], off offset:896
	v_mfma_f32_32x32x16_bf16 v[0:15], v[212:215], v[208:211], v[0:15]
	global_load_dwordx4 v[78:81], v[146:147], off offset:896
	s_waitcnt lgkmcnt(3)
	v_mfma_f32_32x32x16_bf16 v[48:63], v[232:235], v[236:239], v[48:63]
	global_load_dwordx4 v[82:85], v[138:139], off offset:896
	s_waitcnt lgkmcnt(1)
	v_mfma_f32_32x32x16_bf16 v[32:47], v[232:235], v[240:243], v[32:47]
	global_load_dwordx4 v[106:109], v[148:149], off offset:896
	s_waitcnt lgkmcnt(0)
	v_mfma_f32_32x32x16_bf16 v[16:31], v[244:247], v[236:239], v[16:31]
	global_load_dwordx4 v[110:113], v[150:151], off offset:896
	v_mfma_f32_32x32x16_bf16 v[0:15], v[244:247], v[240:243], v[0:15]
	global_load_dwordx4 v[122:125], v[152:153], off offset:896
	s_setprio 0
	s_waitcnt lgkmcnt(0)
	s_barrier
	s_setprio 1
	ds_read_b128 v[200:203], v134 offset:36864
	ds_read_b128 v[204:207], v156 offset:55296
	ds_read_b128 v[208:211], v156 offset:59904
	ds_read_b128 v[212:215], v134 offset:41472
	ds_read_b128 v[232:235], v134 offset:36896
	ds_read_b128 v[236:239], v156 offset:55328
	ds_read_b128 v[240:243], v156 offset:59936
	ds_read_b128 v[244:247], v134 offset:41504
	s_waitcnt lgkmcnt(6)
	v_mfma_f32_32x32x16_bf16 v[48:63], v[200:203], v[204:207], v[48:63]
	s_waitcnt lgkmcnt(5)
	v_mfma_f32_32x32x16_bf16 v[32:47], v[200:203], v[208:211], v[32:47]
	s_waitcnt vmcnt(15)
	ds_write_b128 v132, v[86:89]
	s_waitcnt vmcnt(14)
	ds_write_b128 v132, v[90:93] offset:4608
	ds_read_b128 v[200:203], v134 offset:36928
	s_waitcnt lgkmcnt(7)
	v_mfma_f32_32x32x16_bf16 v[16:31], v[212:215], v[204:207], v[16:31]
	s_waitcnt vmcnt(13)
	ds_write_b128 v132, v[94:97] offset:9216
	ds_read_b128 v[204:207], v156 offset:55360
	v_mfma_f32_32x32x16_bf16 v[0:15], v[212:215], v[208:211], v[0:15]
	s_waitcnt vmcnt(12)
	ds_write_b128 v132, v[98:101] offset:13824
	ds_read_b128 v[208:211], v156 offset:59968
	ds_read_b128 v[212:215], v134 offset:41536
	s_waitcnt lgkmcnt(10)
	v_mfma_f32_32x32x16_bf16 v[48:63], v[232:235], v[236:239], v[48:63]
	s_waitcnt vmcnt(11)
	ds_write_b128 v132, v[102:105] offset:18432
	s_waitcnt lgkmcnt(10)
	v_mfma_f32_32x32x16_bf16 v[32:47], v[232:235], v[240:243], v[32:47]
	s_waitcnt vmcnt(10)
	ds_write_b128 v132, v[114:117] offset:23040
	ds_read_b128 v[232:235], v134 offset:36960
	s_waitcnt lgkmcnt(11)
	v_mfma_f32_32x32x16_bf16 v[16:31], v[244:247], v[236:239], v[16:31]
	s_waitcnt vmcnt(9)
	ds_write_b128 v132, v[118:121] offset:27648
	ds_read_b128 v[236:239], v156 offset:55392
	v_mfma_f32_32x32x16_bf16 v[0:15], v[244:247], v[240:243], v[0:15]
	s_waitcnt vmcnt(8)
	ds_write_b128 v132, v[126:129] offset:32256
	ds_read_b128 v[240:243], v156 offset:60000
	ds_read_b128 v[244:247], v134 offset:41568
	s_waitcnt lgkmcnt(11)
	v_mfma_f32_32x32x16_bf16 v[48:63], v[200:203], v[204:207], v[48:63]
	global_load_dwordx4 v[86:89], v[140:141], off offset:1024
	s_waitcnt lgkmcnt(9)
	v_mfma_f32_32x32x16_bf16 v[32:47], v[200:203], v[208:211], v[32:47]
	global_load_dwordx4 v[90:93], v[142:143], off offset:1024
	s_waitcnt lgkmcnt(8)
	v_mfma_f32_32x32x16_bf16 v[16:31], v[212:215], v[204:207], v[16:31]
	global_load_dwordx4 v[94:97], v[144:145], off offset:1024
	v_mfma_f32_32x32x16_bf16 v[0:15], v[212:215], v[208:211], v[0:15]
	global_load_dwordx4 v[98:101], v[146:147], off offset:1024
	s_waitcnt lgkmcnt(3)
	v_mfma_f32_32x32x16_bf16 v[48:63], v[232:235], v[236:239], v[48:63]
	global_load_dwordx4 v[102:105], v[138:139], off offset:1024
	s_waitcnt lgkmcnt(1)
	v_mfma_f32_32x32x16_bf16 v[32:47], v[232:235], v[240:243], v[32:47]
	global_load_dwordx4 v[114:117], v[148:149], off offset:1024
	s_waitcnt lgkmcnt(0)
	v_mfma_f32_32x32x16_bf16 v[16:31], v[244:247], v[236:239], v[16:31]
	global_load_dwordx4 v[118:121], v[150:151], off offset:1024
	v_mfma_f32_32x32x16_bf16 v[0:15], v[244:247], v[240:243], v[0:15]
	global_load_dwordx4 v[126:129], v[152:153], off offset:1024
	s_setprio 0
	s_waitcnt lgkmcnt(0)
	s_barrier
	s_setprio 1
	ds_read_b128 v[200:203], v134
	ds_read_b128 v[204:207], v156 offset:18432
	ds_read_b128 v[208:211], v156 offset:23040
	ds_read_b128 v[212:215], v134 offset:4608
	ds_read_b128 v[232:235], v134 offset:32
	ds_read_b128 v[236:239], v156 offset:18464
	ds_read_b128 v[240:243], v156 offset:23072
	ds_read_b128 v[244:247], v134 offset:4640
	s_waitcnt lgkmcnt(6)
	v_mfma_f32_32x32x16_bf16 v[48:63], v[200:203], v[204:207], v[48:63]
	s_waitcnt lgkmcnt(5)
	v_mfma_f32_32x32x16_bf16 v[32:47], v[200:203], v[208:211], v[32:47]
	s_waitcnt vmcnt(15)
	ds_write_b128 v132, v[66:69] offset:36864
	s_waitcnt vmcnt(14)
	ds_write_b128 v132, v[70:73] offset:41472
	ds_read_b128 v[200:203], v134 offset:64
	s_waitcnt lgkmcnt(7)
	v_mfma_f32_32x32x16_bf16 v[16:31], v[212:215], v[204:207], v[16:31]
	s_waitcnt vmcnt(13)
	ds_write_b128 v132, v[74:77] offset:46080
	ds_read_b128 v[204:207], v156 offset:18496
	v_mfma_f32_32x32x16_bf16 v[0:15], v[212:215], v[208:211], v[0:15]
	s_waitcnt vmcnt(12)
	ds_write_b128 v132, v[78:81] offset:50688
	ds_read_b128 v[208:211], v156 offset:23104
	ds_read_b128 v[212:215], v134 offset:4672
	s_waitcnt lgkmcnt(10)
	v_mfma_f32_32x32x16_bf16 v[48:63], v[232:235], v[236:239], v[48:63]
	s_waitcnt vmcnt(11)
	ds_write_b128 v132, v[82:85] offset:55296
	s_waitcnt lgkmcnt(10)
	v_mfma_f32_32x32x16_bf16 v[32:47], v[232:235], v[240:243], v[32:47]
	s_waitcnt vmcnt(10)
	ds_write_b128 v132, v[106:109] offset:59904
	ds_read_b128 v[232:235], v134 offset:96
	s_waitcnt lgkmcnt(11)
	v_mfma_f32_32x32x16_bf16 v[16:31], v[244:247], v[236:239], v[16:31]
	s_waitcnt vmcnt(9)
	ds_write_b128 v132, v[110:113] offset:64512
	ds_read_b128 v[236:239], v156 offset:18528
	v_mfma_f32_32x32x16_bf16 v[0:15], v[244:247], v[240:243], v[0:15]
	s_waitcnt vmcnt(8)
	ds_write_b128 v133, v[122:125] offset:32256
	ds_read_b128 v[240:243], v156 offset:23136
	ds_read_b128 v[244:247], v134 offset:4704
	s_waitcnt lgkmcnt(11)
	v_mfma_f32_32x32x16_bf16 v[48:63], v[200:203], v[204:207], v[48:63]
	global_load_dwordx4 v[66:69], v[140:141], off offset:1152
	s_waitcnt lgkmcnt(9)
	v_mfma_f32_32x32x16_bf16 v[32:47], v[200:203], v[208:211], v[32:47]
	global_load_dwordx4 v[70:73], v[142:143], off offset:1152
	s_waitcnt lgkmcnt(8)
	v_mfma_f32_32x32x16_bf16 v[16:31], v[212:215], v[204:207], v[16:31]
	global_load_dwordx4 v[74:77], v[144:145], off offset:1152
	v_mfma_f32_32x32x16_bf16 v[0:15], v[212:215], v[208:211], v[0:15]
	global_load_dwordx4 v[78:81], v[146:147], off offset:1152
	s_waitcnt lgkmcnt(3)
	v_mfma_f32_32x32x16_bf16 v[48:63], v[232:235], v[236:239], v[48:63]
	global_load_dwordx4 v[82:85], v[138:139], off offset:1152
	s_waitcnt lgkmcnt(1)
	v_mfma_f32_32x32x16_bf16 v[32:47], v[232:235], v[240:243], v[32:47]
	global_load_dwordx4 v[106:109], v[148:149], off offset:1152
	s_waitcnt lgkmcnt(0)
	v_mfma_f32_32x32x16_bf16 v[16:31], v[244:247], v[236:239], v[16:31]
	global_load_dwordx4 v[110:113], v[150:151], off offset:1152
	v_mfma_f32_32x32x16_bf16 v[0:15], v[244:247], v[240:243], v[0:15]
	global_load_dwordx4 v[122:125], v[152:153], off offset:1152
	s_setprio 0
	s_waitcnt lgkmcnt(0)
	s_barrier
	s_setprio 1
	ds_read_b128 v[200:203], v134 offset:36864
	ds_read_b128 v[204:207], v156 offset:55296
	ds_read_b128 v[208:211], v156 offset:59904
	ds_read_b128 v[212:215], v134 offset:41472
	ds_read_b128 v[232:235], v134 offset:36896
	ds_read_b128 v[236:239], v156 offset:55328
	ds_read_b128 v[240:243], v156 offset:59936
	ds_read_b128 v[244:247], v134 offset:41504
	s_waitcnt lgkmcnt(6)
	v_mfma_f32_32x32x16_bf16 v[48:63], v[200:203], v[204:207], v[48:63]
	s_waitcnt lgkmcnt(5)
	v_mfma_f32_32x32x16_bf16 v[32:47], v[200:203], v[208:211], v[32:47]
	s_waitcnt vmcnt(15)
	ds_write_b128 v132, v[86:89]
	s_waitcnt vmcnt(14)
	ds_write_b128 v132, v[90:93] offset:4608
	ds_read_b128 v[200:203], v134 offset:36928
	s_waitcnt lgkmcnt(7)
	v_mfma_f32_32x32x16_bf16 v[16:31], v[212:215], v[204:207], v[16:31]
	s_waitcnt vmcnt(13)
	ds_write_b128 v132, v[94:97] offset:9216
	ds_read_b128 v[204:207], v156 offset:55360
	v_mfma_f32_32x32x16_bf16 v[0:15], v[212:215], v[208:211], v[0:15]
	s_waitcnt vmcnt(12)
	ds_write_b128 v132, v[98:101] offset:13824
	ds_read_b128 v[208:211], v156 offset:59968
	ds_read_b128 v[212:215], v134 offset:41536
	s_waitcnt lgkmcnt(10)
	v_mfma_f32_32x32x16_bf16 v[48:63], v[232:235], v[236:239], v[48:63]
	s_waitcnt vmcnt(11)
	ds_write_b128 v132, v[102:105] offset:18432
	s_waitcnt lgkmcnt(10)
	v_mfma_f32_32x32x16_bf16 v[32:47], v[232:235], v[240:243], v[32:47]
	s_waitcnt vmcnt(10)
	ds_write_b128 v132, v[114:117] offset:23040
	ds_read_b128 v[232:235], v134 offset:36960
	s_waitcnt lgkmcnt(11)
	v_mfma_f32_32x32x16_bf16 v[16:31], v[244:247], v[236:239], v[16:31]
	s_waitcnt vmcnt(9)
	ds_write_b128 v132, v[118:121] offset:27648
	ds_read_b128 v[236:239], v156 offset:55392
	v_mfma_f32_32x32x16_bf16 v[0:15], v[244:247], v[240:243], v[0:15]
	s_waitcnt vmcnt(8)
	ds_write_b128 v132, v[126:129] offset:32256
	ds_read_b128 v[240:243], v156 offset:60000
	ds_read_b128 v[244:247], v134 offset:41568
	s_waitcnt lgkmcnt(11)
	v_mfma_f32_32x32x16_bf16 v[48:63], v[200:203], v[204:207], v[48:63]
	global_load_dwordx4 v[86:89], v[140:141], off offset:1280
	s_waitcnt lgkmcnt(9)
	v_mfma_f32_32x32x16_bf16 v[32:47], v[200:203], v[208:211], v[32:47]
	global_load_dwordx4 v[90:93], v[142:143], off offset:1280
	s_waitcnt lgkmcnt(8)
	v_mfma_f32_32x32x16_bf16 v[16:31], v[212:215], v[204:207], v[16:31]
	global_load_dwordx4 v[94:97], v[144:145], off offset:1280
	v_mfma_f32_32x32x16_bf16 v[0:15], v[212:215], v[208:211], v[0:15]
	global_load_dwordx4 v[98:101], v[146:147], off offset:1280
	s_waitcnt lgkmcnt(3)
	v_mfma_f32_32x32x16_bf16 v[48:63], v[232:235], v[236:239], v[48:63]
	global_load_dwordx4 v[102:105], v[138:139], off offset:1280
	s_waitcnt lgkmcnt(1)
	v_mfma_f32_32x32x16_bf16 v[32:47], v[232:235], v[240:243], v[32:47]
	global_load_dwordx4 v[114:117], v[148:149], off offset:1280
	s_waitcnt lgkmcnt(0)
	v_mfma_f32_32x32x16_bf16 v[16:31], v[244:247], v[236:239], v[16:31]
	global_load_dwordx4 v[118:121], v[150:151], off offset:1280
	v_mfma_f32_32x32x16_bf16 v[0:15], v[244:247], v[240:243], v[0:15]
	global_load_dwordx4 v[126:129], v[152:153], off offset:1280
	s_setprio 0
	s_waitcnt lgkmcnt(0)
	s_barrier
	s_setprio 1
	ds_read_b128 v[200:203], v134
	ds_read_b128 v[204:207], v156 offset:18432
	ds_read_b128 v[208:211], v156 offset:23040
	ds_read_b128 v[212:215], v134 offset:4608
	ds_read_b128 v[232:235], v134 offset:32
	ds_read_b128 v[236:239], v156 offset:18464
	ds_read_b128 v[240:243], v156 offset:23072
	ds_read_b128 v[244:247], v134 offset:4640
	s_waitcnt lgkmcnt(6)
	v_mfma_f32_32x32x16_bf16 v[48:63], v[200:203], v[204:207], v[48:63]
	s_waitcnt lgkmcnt(5)
	v_mfma_f32_32x32x16_bf16 v[32:47], v[200:203], v[208:211], v[32:47]
	s_waitcnt vmcnt(15)
	ds_write_b128 v132, v[66:69] offset:36864
	s_waitcnt vmcnt(14)
	ds_write_b128 v132, v[70:73] offset:41472
	ds_read_b128 v[200:203], v134 offset:64
	s_waitcnt lgkmcnt(7)
	v_mfma_f32_32x32x16_bf16 v[16:31], v[212:215], v[204:207], v[16:31]
	s_waitcnt vmcnt(13)
	ds_write_b128 v132, v[74:77] offset:46080
	ds_read_b128 v[204:207], v156 offset:18496
	v_mfma_f32_32x32x16_bf16 v[0:15], v[212:215], v[208:211], v[0:15]
	s_waitcnt vmcnt(12)
	ds_write_b128 v132, v[78:81] offset:50688
	ds_read_b128 v[208:211], v156 offset:23104
	ds_read_b128 v[212:215], v134 offset:4672
	s_waitcnt lgkmcnt(10)
	v_mfma_f32_32x32x16_bf16 v[48:63], v[232:235], v[236:239], v[48:63]
	s_waitcnt vmcnt(11)
	ds_write_b128 v132, v[82:85] offset:55296
	s_waitcnt lgkmcnt(10)
	v_mfma_f32_32x32x16_bf16 v[32:47], v[232:235], v[240:243], v[32:47]
	s_waitcnt vmcnt(10)
	ds_write_b128 v132, v[106:109] offset:59904
	ds_read_b128 v[232:235], v134 offset:96
	s_waitcnt lgkmcnt(11)
	v_mfma_f32_32x32x16_bf16 v[16:31], v[244:247], v[236:239], v[16:31]
	s_waitcnt vmcnt(9)
	ds_write_b128 v132, v[110:113] offset:64512
	ds_read_b128 v[236:239], v156 offset:18528
	v_mfma_f32_32x32x16_bf16 v[0:15], v[244:247], v[240:243], v[0:15]
	s_waitcnt vmcnt(8)
	ds_write_b128 v133, v[122:125] offset:32256
	ds_read_b128 v[240:243], v156 offset:23136
	ds_read_b128 v[244:247], v134 offset:4704
	s_waitcnt lgkmcnt(11)
	v_mfma_f32_32x32x16_bf16 v[48:63], v[200:203], v[204:207], v[48:63]
	global_load_dwordx4 v[66:69], v[140:141], off offset:1408
	s_waitcnt lgkmcnt(9)
	v_mfma_f32_32x32x16_bf16 v[32:47], v[200:203], v[208:211], v[32:47]
	global_load_dwordx4 v[70:73], v[142:143], off offset:1408
	s_waitcnt lgkmcnt(8)
	v_mfma_f32_32x32x16_bf16 v[16:31], v[212:215], v[204:207], v[16:31]
	global_load_dwordx4 v[74:77], v[144:145], off offset:1408
	v_mfma_f32_32x32x16_bf16 v[0:15], v[212:215], v[208:211], v[0:15]
	global_load_dwordx4 v[78:81], v[146:147], off offset:1408
	s_waitcnt lgkmcnt(3)
	v_mfma_f32_32x32x16_bf16 v[48:63], v[232:235], v[236:239], v[48:63]
	global_load_dwordx4 v[82:85], v[138:139], off offset:1408
	s_waitcnt lgkmcnt(1)
	v_mfma_f32_32x32x16_bf16 v[32:47], v[232:235], v[240:243], v[32:47]
	global_load_dwordx4 v[106:109], v[148:149], off offset:1408
	s_waitcnt lgkmcnt(0)
	v_mfma_f32_32x32x16_bf16 v[16:31], v[244:247], v[236:239], v[16:31]
	global_load_dwordx4 v[110:113], v[150:151], off offset:1408
	v_mfma_f32_32x32x16_bf16 v[0:15], v[244:247], v[240:243], v[0:15]
	global_load_dwordx4 v[122:125], v[152:153], off offset:1408
	s_setprio 0
	s_waitcnt lgkmcnt(0)
	s_barrier
	s_setprio 1
	ds_read_b128 v[200:203], v134 offset:36864
	ds_read_b128 v[204:207], v156 offset:55296
	ds_read_b128 v[208:211], v156 offset:59904
	ds_read_b128 v[212:215], v134 offset:41472
	ds_read_b128 v[232:235], v134 offset:36896
	ds_read_b128 v[236:239], v156 offset:55328
	ds_read_b128 v[240:243], v156 offset:59936
	ds_read_b128 v[244:247], v134 offset:41504
	s_waitcnt lgkmcnt(6)
	v_mfma_f32_32x32x16_bf16 v[48:63], v[200:203], v[204:207], v[48:63]
	s_waitcnt lgkmcnt(5)
	v_mfma_f32_32x32x16_bf16 v[32:47], v[200:203], v[208:211], v[32:47]
	s_waitcnt vmcnt(15)
	ds_write_b128 v132, v[86:89]
	s_waitcnt vmcnt(14)
	ds_write_b128 v132, v[90:93] offset:4608
	ds_read_b128 v[200:203], v134 offset:36928
	s_waitcnt lgkmcnt(7)
	v_mfma_f32_32x32x16_bf16 v[16:31], v[212:215], v[204:207], v[16:31]
	s_waitcnt vmcnt(13)
	ds_write_b128 v132, v[94:97] offset:9216
	ds_read_b128 v[204:207], v156 offset:55360
	v_mfma_f32_32x32x16_bf16 v[0:15], v[212:215], v[208:211], v[0:15]
	s_waitcnt vmcnt(12)
	ds_write_b128 v132, v[98:101] offset:13824
	ds_read_b128 v[208:211], v156 offset:59968
	ds_read_b128 v[212:215], v134 offset:41536
	s_waitcnt lgkmcnt(10)
	v_mfma_f32_32x32x16_bf16 v[48:63], v[232:235], v[236:239], v[48:63]
	s_waitcnt vmcnt(11)
	ds_write_b128 v132, v[102:105] offset:18432
	s_waitcnt lgkmcnt(10)
	v_mfma_f32_32x32x16_bf16 v[32:47], v[232:235], v[240:243], v[32:47]
	s_waitcnt vmcnt(10)
	ds_write_b128 v132, v[114:117] offset:23040
	ds_read_b128 v[232:235], v134 offset:36960
	s_waitcnt lgkmcnt(11)
	v_mfma_f32_32x32x16_bf16 v[16:31], v[244:247], v[236:239], v[16:31]
	s_waitcnt vmcnt(9)
	ds_write_b128 v132, v[118:121] offset:27648
	ds_read_b128 v[236:239], v156 offset:55392
	v_mfma_f32_32x32x16_bf16 v[0:15], v[244:247], v[240:243], v[0:15]
	s_waitcnt vmcnt(8)
	ds_write_b128 v132, v[126:129] offset:32256
	ds_read_b128 v[240:243], v156 offset:60000
	ds_read_b128 v[244:247], v134 offset:41568
	s_waitcnt lgkmcnt(11)
	v_mfma_f32_32x32x16_bf16 v[48:63], v[200:203], v[204:207], v[48:63]
	global_load_dwordx4 v[86:89], v[140:141], off offset:1536
	s_waitcnt lgkmcnt(9)
	v_mfma_f32_32x32x16_bf16 v[32:47], v[200:203], v[208:211], v[32:47]
	global_load_dwordx4 v[90:93], v[142:143], off offset:1536
	s_waitcnt lgkmcnt(8)
	v_mfma_f32_32x32x16_bf16 v[16:31], v[212:215], v[204:207], v[16:31]
	global_load_dwordx4 v[94:97], v[144:145], off offset:1536
	v_mfma_f32_32x32x16_bf16 v[0:15], v[212:215], v[208:211], v[0:15]
	global_load_dwordx4 v[98:101], v[146:147], off offset:1536
	s_waitcnt lgkmcnt(3)
	v_mfma_f32_32x32x16_bf16 v[48:63], v[232:235], v[236:239], v[48:63]
	global_load_dwordx4 v[102:105], v[138:139], off offset:1536
	s_waitcnt lgkmcnt(1)
	v_mfma_f32_32x32x16_bf16 v[32:47], v[232:235], v[240:243], v[32:47]
	global_load_dwordx4 v[114:117], v[148:149], off offset:1536
	s_waitcnt lgkmcnt(0)
	v_mfma_f32_32x32x16_bf16 v[16:31], v[244:247], v[236:239], v[16:31]
	global_load_dwordx4 v[118:121], v[150:151], off offset:1536
	v_mfma_f32_32x32x16_bf16 v[0:15], v[244:247], v[240:243], v[0:15]
	global_load_dwordx4 v[126:129], v[152:153], off offset:1536
	s_setprio 0
	s_waitcnt lgkmcnt(0)
	s_barrier
	s_setprio 1
	ds_read_b128 v[200:203], v134
	ds_read_b128 v[204:207], v156 offset:18432
	ds_read_b128 v[208:211], v156 offset:23040
	ds_read_b128 v[212:215], v134 offset:4608
	ds_read_b128 v[232:235], v134 offset:32
	ds_read_b128 v[236:239], v156 offset:18464
	ds_read_b128 v[240:243], v156 offset:23072
	ds_read_b128 v[244:247], v134 offset:4640
	s_waitcnt lgkmcnt(6)
	v_mfma_f32_32x32x16_bf16 v[48:63], v[200:203], v[204:207], v[48:63]
	s_waitcnt lgkmcnt(5)
	v_mfma_f32_32x32x16_bf16 v[32:47], v[200:203], v[208:211], v[32:47]
	s_waitcnt vmcnt(15)
	ds_write_b128 v132, v[66:69] offset:36864
	s_waitcnt vmcnt(14)
	ds_write_b128 v132, v[70:73] offset:41472
	ds_read_b128 v[200:203], v134 offset:64
	s_waitcnt lgkmcnt(7)
	v_mfma_f32_32x32x16_bf16 v[16:31], v[212:215], v[204:207], v[16:31]
	s_waitcnt vmcnt(13)
	ds_write_b128 v132, v[74:77] offset:46080
	ds_read_b128 v[204:207], v156 offset:18496
	v_mfma_f32_32x32x16_bf16 v[0:15], v[212:215], v[208:211], v[0:15]
	s_waitcnt vmcnt(12)
	ds_write_b128 v132, v[78:81] offset:50688
	ds_read_b128 v[208:211], v156 offset:23104
	ds_read_b128 v[212:215], v134 offset:4672
	s_waitcnt lgkmcnt(10)
	v_mfma_f32_32x32x16_bf16 v[48:63], v[232:235], v[236:239], v[48:63]
	s_waitcnt vmcnt(11)
	ds_write_b128 v132, v[82:85] offset:55296
	s_waitcnt lgkmcnt(10)
	v_mfma_f32_32x32x16_bf16 v[32:47], v[232:235], v[240:243], v[32:47]
	s_waitcnt vmcnt(10)
	ds_write_b128 v132, v[106:109] offset:59904
	ds_read_b128 v[232:235], v134 offset:96
	s_waitcnt lgkmcnt(11)
	v_mfma_f32_32x32x16_bf16 v[16:31], v[244:247], v[236:239], v[16:31]
	s_waitcnt vmcnt(9)
	ds_write_b128 v132, v[110:113] offset:64512
	ds_read_b128 v[236:239], v156 offset:18528
	v_mfma_f32_32x32x16_bf16 v[0:15], v[244:247], v[240:243], v[0:15]
	s_waitcnt vmcnt(8)
	ds_write_b128 v133, v[122:125] offset:32256
	ds_read_b128 v[240:243], v156 offset:23136
	ds_read_b128 v[244:247], v134 offset:4704
	s_waitcnt lgkmcnt(11)
	v_mfma_f32_32x32x16_bf16 v[48:63], v[200:203], v[204:207], v[48:63]
	global_load_dwordx4 v[66:69], v[140:141], off offset:1664
	s_waitcnt lgkmcnt(9)
	v_mfma_f32_32x32x16_bf16 v[32:47], v[200:203], v[208:211], v[32:47]
	global_load_dwordx4 v[70:73], v[142:143], off offset:1664
	s_waitcnt lgkmcnt(8)
	v_mfma_f32_32x32x16_bf16 v[16:31], v[212:215], v[204:207], v[16:31]
	global_load_dwordx4 v[74:77], v[144:145], off offset:1664
	v_mfma_f32_32x32x16_bf16 v[0:15], v[212:215], v[208:211], v[0:15]
	global_load_dwordx4 v[78:81], v[146:147], off offset:1664
	s_waitcnt lgkmcnt(3)
	v_mfma_f32_32x32x16_bf16 v[48:63], v[232:235], v[236:239], v[48:63]
	global_load_dwordx4 v[82:85], v[138:139], off offset:1664
	s_waitcnt lgkmcnt(1)
	v_mfma_f32_32x32x16_bf16 v[32:47], v[232:235], v[240:243], v[32:47]
	global_load_dwordx4 v[106:109], v[148:149], off offset:1664
	s_waitcnt lgkmcnt(0)
	v_mfma_f32_32x32x16_bf16 v[16:31], v[244:247], v[236:239], v[16:31]
	global_load_dwordx4 v[110:113], v[150:151], off offset:1664
	v_mfma_f32_32x32x16_bf16 v[0:15], v[244:247], v[240:243], v[0:15]
	global_load_dwordx4 v[122:125], v[152:153], off offset:1664
	s_setprio 0
	s_waitcnt lgkmcnt(0)
	s_barrier
	s_setprio 1
	ds_read_b128 v[200:203], v134 offset:36864
	ds_read_b128 v[204:207], v156 offset:55296
	ds_read_b128 v[208:211], v156 offset:59904
	ds_read_b128 v[212:215], v134 offset:41472
	ds_read_b128 v[232:235], v134 offset:36896
	ds_read_b128 v[236:239], v156 offset:55328
	ds_read_b128 v[240:243], v156 offset:59936
	ds_read_b128 v[244:247], v134 offset:41504
	s_waitcnt lgkmcnt(6)
	v_mfma_f32_32x32x16_bf16 v[48:63], v[200:203], v[204:207], v[48:63]
	s_waitcnt lgkmcnt(5)
	v_mfma_f32_32x32x16_bf16 v[32:47], v[200:203], v[208:211], v[32:47]
	s_waitcnt vmcnt(15)
	ds_write_b128 v132, v[86:89]
	s_waitcnt vmcnt(14)
	ds_write_b128 v132, v[90:93] offset:4608
	ds_read_b128 v[200:203], v134 offset:36928
	s_waitcnt lgkmcnt(7)
	v_mfma_f32_32x32x16_bf16 v[16:31], v[212:215], v[204:207], v[16:31]
	s_waitcnt vmcnt(13)
	ds_write_b128 v132, v[94:97] offset:9216
	ds_read_b128 v[204:207], v156 offset:55360
	v_mfma_f32_32x32x16_bf16 v[0:15], v[212:215], v[208:211], v[0:15]
	s_waitcnt vmcnt(12)
	ds_write_b128 v132, v[98:101] offset:13824
	ds_read_b128 v[208:211], v156 offset:59968
	ds_read_b128 v[212:215], v134 offset:41536
	s_waitcnt lgkmcnt(10)
	v_mfma_f32_32x32x16_bf16 v[48:63], v[232:235], v[236:239], v[48:63]
	s_waitcnt vmcnt(11)
	ds_write_b128 v132, v[102:105] offset:18432
	s_waitcnt lgkmcnt(10)
	v_mfma_f32_32x32x16_bf16 v[32:47], v[232:235], v[240:243], v[32:47]
	s_waitcnt vmcnt(10)
	ds_write_b128 v132, v[114:117] offset:23040
	ds_read_b128 v[232:235], v134 offset:36960
	s_waitcnt lgkmcnt(11)
	v_mfma_f32_32x32x16_bf16 v[16:31], v[244:247], v[236:239], v[16:31]
	s_waitcnt vmcnt(9)
	ds_write_b128 v132, v[118:121] offset:27648
	ds_read_b128 v[236:239], v156 offset:55392
	v_mfma_f32_32x32x16_bf16 v[0:15], v[244:247], v[240:243], v[0:15]
	s_waitcnt vmcnt(8)
	ds_write_b128 v132, v[126:129] offset:32256
	ds_read_b128 v[240:243], v156 offset:60000
	ds_read_b128 v[244:247], v134 offset:41568
	s_waitcnt lgkmcnt(11)
	v_mfma_f32_32x32x16_bf16 v[48:63], v[200:203], v[204:207], v[48:63]
	global_load_dwordx4 v[86:89], v[140:141], off offset:1792
	s_waitcnt lgkmcnt(9)
	v_mfma_f32_32x32x16_bf16 v[32:47], v[200:203], v[208:211], v[32:47]
	global_load_dwordx4 v[90:93], v[142:143], off offset:1792
	s_waitcnt lgkmcnt(8)
	v_mfma_f32_32x32x16_bf16 v[16:31], v[212:215], v[204:207], v[16:31]
	global_load_dwordx4 v[94:97], v[144:145], off offset:1792
	v_mfma_f32_32x32x16_bf16 v[0:15], v[212:215], v[208:211], v[0:15]
	global_load_dwordx4 v[98:101], v[146:147], off offset:1792
	s_waitcnt lgkmcnt(3)
	v_mfma_f32_32x32x16_bf16 v[48:63], v[232:235], v[236:239], v[48:63]
	global_load_dwordx4 v[102:105], v[138:139], off offset:1792
	s_waitcnt lgkmcnt(1)
	v_mfma_f32_32x32x16_bf16 v[32:47], v[232:235], v[240:243], v[32:47]
	global_load_dwordx4 v[114:117], v[148:149], off offset:1792
	s_waitcnt lgkmcnt(0)
	v_mfma_f32_32x32x16_bf16 v[16:31], v[244:247], v[236:239], v[16:31]
	global_load_dwordx4 v[118:121], v[150:151], off offset:1792
	v_mfma_f32_32x32x16_bf16 v[0:15], v[244:247], v[240:243], v[0:15]
	global_load_dwordx4 v[126:129], v[152:153], off offset:1792
	s_setprio 0
	s_waitcnt lgkmcnt(0)
	s_barrier
	s_setprio 1
	ds_read_b128 v[200:203], v134
	ds_read_b128 v[204:207], v156 offset:18432
	ds_read_b128 v[208:211], v156 offset:23040
	ds_read_b128 v[212:215], v134 offset:4608
	ds_read_b128 v[232:235], v134 offset:32
	ds_read_b128 v[236:239], v156 offset:18464
	ds_read_b128 v[240:243], v156 offset:23072
	ds_read_b128 v[244:247], v134 offset:4640
	s_waitcnt lgkmcnt(6)
	v_mfma_f32_32x32x16_bf16 v[48:63], v[200:203], v[204:207], v[48:63]
	s_waitcnt lgkmcnt(5)
	v_mfma_f32_32x32x16_bf16 v[32:47], v[200:203], v[208:211], v[32:47]
	s_waitcnt vmcnt(15)
	ds_write_b128 v132, v[66:69] offset:36864
	s_waitcnt vmcnt(14)
	ds_write_b128 v132, v[70:73] offset:41472
	ds_read_b128 v[200:203], v134 offset:64
	s_waitcnt lgkmcnt(7)
	v_mfma_f32_32x32x16_bf16 v[16:31], v[212:215], v[204:207], v[16:31]
	s_waitcnt vmcnt(13)
	ds_write_b128 v132, v[74:77] offset:46080
	ds_read_b128 v[204:207], v156 offset:18496
	v_mfma_f32_32x32x16_bf16 v[0:15], v[212:215], v[208:211], v[0:15]
	s_waitcnt vmcnt(12)
	ds_write_b128 v132, v[78:81] offset:50688
	ds_read_b128 v[208:211], v156 offset:23104
	ds_read_b128 v[212:215], v134 offset:4672
	s_waitcnt lgkmcnt(10)
	v_mfma_f32_32x32x16_bf16 v[48:63], v[232:235], v[236:239], v[48:63]
	s_waitcnt vmcnt(11)
	ds_write_b128 v132, v[82:85] offset:55296
	s_waitcnt lgkmcnt(10)
	v_mfma_f32_32x32x16_bf16 v[32:47], v[232:235], v[240:243], v[32:47]
	s_waitcnt vmcnt(10)
	ds_write_b128 v132, v[106:109] offset:59904
	ds_read_b128 v[232:235], v134 offset:96
	s_waitcnt lgkmcnt(11)
	v_mfma_f32_32x32x16_bf16 v[16:31], v[244:247], v[236:239], v[16:31]
	s_waitcnt vmcnt(9)
	ds_write_b128 v132, v[110:113] offset:64512
	ds_read_b128 v[236:239], v156 offset:18528
	v_mfma_f32_32x32x16_bf16 v[0:15], v[244:247], v[240:243], v[0:15]
	s_waitcnt vmcnt(8)
	ds_write_b128 v133, v[122:125] offset:32256
	ds_read_b128 v[240:243], v156 offset:23136
	ds_read_b128 v[244:247], v134 offset:4704
	s_waitcnt lgkmcnt(11)
	v_mfma_f32_32x32x16_bf16 v[48:63], v[200:203], v[204:207], v[48:63]
	global_load_dwordx4 v[66:69], v[140:141], off offset:1920
	s_waitcnt lgkmcnt(9)
	v_mfma_f32_32x32x16_bf16 v[32:47], v[200:203], v[208:211], v[32:47]
	global_load_dwordx4 v[70:73], v[142:143], off offset:1920
	s_waitcnt lgkmcnt(8)
	v_mfma_f32_32x32x16_bf16 v[16:31], v[212:215], v[204:207], v[16:31]
	global_load_dwordx4 v[74:77], v[144:145], off offset:1920
	v_mfma_f32_32x32x16_bf16 v[0:15], v[212:215], v[208:211], v[0:15]
	global_load_dwordx4 v[78:81], v[146:147], off offset:1920
	s_waitcnt lgkmcnt(3)
	v_mfma_f32_32x32x16_bf16 v[48:63], v[232:235], v[236:239], v[48:63]
	global_load_dwordx4 v[82:85], v[138:139], off offset:1920
	s_waitcnt lgkmcnt(1)
	v_mfma_f32_32x32x16_bf16 v[32:47], v[232:235], v[240:243], v[32:47]
	global_load_dwordx4 v[106:109], v[148:149], off offset:1920
	s_waitcnt lgkmcnt(0)
	v_mfma_f32_32x32x16_bf16 v[16:31], v[244:247], v[236:239], v[16:31]
	global_load_dwordx4 v[110:113], v[150:151], off offset:1920
	v_mfma_f32_32x32x16_bf16 v[0:15], v[244:247], v[240:243], v[0:15]
	global_load_dwordx4 v[122:125], v[152:153], off offset:1920
	s_setprio 0
	s_waitcnt lgkmcnt(0)
	s_barrier
	s_setprio 1
	ds_read_b128 v[200:203], v134 offset:36864
	ds_read_b128 v[204:207], v156 offset:55296
	ds_read_b128 v[208:211], v156 offset:59904
	ds_read_b128 v[212:215], v134 offset:41472
	ds_read_b128 v[232:235], v134 offset:36896
	ds_read_b128 v[236:239], v156 offset:55328
	ds_read_b128 v[240:243], v156 offset:59936
	ds_read_b128 v[244:247], v134 offset:41504
	s_waitcnt lgkmcnt(6)
	v_mfma_f32_32x32x16_bf16 v[48:63], v[200:203], v[204:207], v[48:63]
	s_waitcnt lgkmcnt(5)
	v_mfma_f32_32x32x16_bf16 v[32:47], v[200:203], v[208:211], v[32:47]
	s_waitcnt vmcnt(15)
	ds_write_b128 v132, v[86:89]
	ds_read_b128 v[200:203], v134 offset:36928
	s_waitcnt lgkmcnt(6)
	v_mfma_f32_32x32x16_bf16 v[16:31], v[212:215], v[204:207], v[16:31]
	s_waitcnt vmcnt(14)
	ds_write_b128 v132, v[90:93] offset:4608
	ds_read_b128 v[204:207], v156 offset:55360
	v_mfma_f32_32x32x16_bf16 v[0:15], v[212:215], v[208:211], v[0:15]
	ds_read_b128 v[208:211], v156 offset:59968
	ds_read_b128 v[212:215], v134 offset:41536
	s_waitcnt lgkmcnt(8)
	v_mfma_f32_32x32x16_bf16 v[48:63], v[232:235], v[236:239], v[48:63]
	s_waitcnt vmcnt(13)
	ds_write_b128 v132, v[94:97] offset:9216
	s_waitcnt lgkmcnt(8)
	v_mfma_f32_32x32x16_bf16 v[32:47], v[232:235], v[240:243], v[32:47]
	ds_read_b128 v[232:235], v134 offset:36960
	s_waitcnt lgkmcnt(8)
	v_mfma_f32_32x32x16_bf16 v[16:31], v[244:247], v[236:239], v[16:31]
	s_waitcnt vmcnt(12)
	ds_write_b128 v132, v[98:101] offset:13824
	ds_read_b128 v[236:239], v156 offset:55392
	v_mfma_f32_32x32x16_bf16 v[0:15], v[244:247], v[240:243], v[0:15]
	ds_read_b128 v[240:243], v156 offset:60000
	ds_read_b128 v[244:247], v134 offset:41568
	s_waitcnt lgkmcnt(8)
	v_mfma_f32_32x32x16_bf16 v[48:63], v[200:203], v[204:207], v[48:63]
	s_waitcnt vmcnt(11)
	ds_write_b128 v132, v[102:105] offset:18432
	s_waitcnt lgkmcnt(8)
	v_mfma_f32_32x32x16_bf16 v[32:47], v[200:203], v[208:211], v[32:47]
	s_waitcnt lgkmcnt(7)
	v_mfma_f32_32x32x16_bf16 v[16:31], v[212:215], v[204:207], v[16:31]
	s_waitcnt vmcnt(10)
	ds_write_b128 v132, v[114:117] offset:23040
	v_mfma_f32_32x32x16_bf16 v[0:15], v[212:215], v[208:211], v[0:15]
	s_waitcnt lgkmcnt(4)
	v_mfma_f32_32x32x16_bf16 v[48:63], v[232:235], v[236:239], v[48:63]
	s_waitcnt vmcnt(9)
	ds_write_b128 v132, v[118:121] offset:27648
	s_waitcnt lgkmcnt(4)
	v_mfma_f32_32x32x16_bf16 v[32:47], v[232:235], v[240:243], v[32:47]
	s_waitcnt lgkmcnt(3)
	v_mfma_f32_32x32x16_bf16 v[16:31], v[244:247], v[236:239], v[16:31]
	s_waitcnt vmcnt(8)
	ds_write_b128 v132, v[126:129] offset:32256
	v_mfma_f32_32x32x16_bf16 v[0:15], v[244:247], v[240:243], v[0:15]
	s_setprio 0
	s_waitcnt lgkmcnt(0)
	s_barrier
	s_setprio 1
	ds_read_b128 v[200:203], v134
	ds_read_b128 v[204:207], v156 offset:18432
	ds_read_b128 v[208:211], v156 offset:23040
	ds_read_b128 v[212:215], v134 offset:4608
	ds_read_b128 v[232:235], v134 offset:32
	ds_read_b128 v[236:239], v156 offset:18464
	ds_read_b128 v[240:243], v156 offset:23072
	ds_read_b128 v[244:247], v134 offset:4640
	s_waitcnt lgkmcnt(6)
	v_mfma_f32_32x32x16_bf16 v[48:63], v[200:203], v[204:207], v[48:63]
	s_waitcnt lgkmcnt(5)
	v_mfma_f32_32x32x16_bf16 v[32:47], v[200:203], v[208:211], v[32:47]
	s_waitcnt vmcnt(7)
	ds_write_b128 v132, v[66:69] offset:36864
	ds_read_b128 v[200:203], v134 offset:64
	s_waitcnt lgkmcnt(6)
	v_mfma_f32_32x32x16_bf16 v[16:31], v[212:215], v[204:207], v[16:31]
	s_waitcnt vmcnt(6)
	ds_write_b128 v132, v[70:73] offset:41472
	ds_read_b128 v[204:207], v156 offset:18496
	v_mfma_f32_32x32x16_bf16 v[0:15], v[212:215], v[208:211], v[0:15]
	ds_read_b128 v[208:211], v156 offset:23104
	ds_read_b128 v[212:215], v134 offset:4672
	s_waitcnt lgkmcnt(8)
	v_mfma_f32_32x32x16_bf16 v[48:63], v[232:235], v[236:239], v[48:63]
	s_waitcnt vmcnt(5)
	ds_write_b128 v132, v[74:77] offset:46080
	s_waitcnt lgkmcnt(8)
	v_mfma_f32_32x32x16_bf16 v[32:47], v[232:235], v[240:243], v[32:47]
	ds_read_b128 v[232:235], v134 offset:96
	s_waitcnt lgkmcnt(8)
	v_mfma_f32_32x32x16_bf16 v[16:31], v[244:247], v[236:239], v[16:31]
	s_waitcnt vmcnt(4)
	ds_write_b128 v132, v[78:81] offset:50688
	ds_read_b128 v[236:239], v156 offset:18528
	v_mfma_f32_32x32x16_bf16 v[0:15], v[244:247], v[240:243], v[0:15]
	ds_read_b128 v[240:243], v156 offset:23136
	ds_read_b128 v[244:247], v134 offset:4704
	s_waitcnt lgkmcnt(8)
	v_mfma_f32_32x32x16_bf16 v[48:63], v[200:203], v[204:207], v[48:63]
	s_waitcnt vmcnt(3)
	ds_write_b128 v132, v[82:85] offset:55296
	s_waitcnt lgkmcnt(8)
	v_mfma_f32_32x32x16_bf16 v[32:47], v[200:203], v[208:211], v[32:47]
	s_waitcnt lgkmcnt(7)
	v_mfma_f32_32x32x16_bf16 v[16:31], v[212:215], v[204:207], v[16:31]
	s_waitcnt vmcnt(2)
	ds_write_b128 v132, v[106:109] offset:59904
	v_mfma_f32_32x32x16_bf16 v[0:15], v[212:215], v[208:211], v[0:15]
	s_waitcnt lgkmcnt(4)
	v_mfma_f32_32x32x16_bf16 v[48:63], v[232:235], v[236:239], v[48:63]
	s_waitcnt vmcnt(1)
	ds_write_b128 v132, v[110:113] offset:64512
	s_waitcnt lgkmcnt(4)
	v_mfma_f32_32x32x16_bf16 v[32:47], v[232:235], v[240:243], v[32:47]
	s_waitcnt lgkmcnt(3)
	v_mfma_f32_32x32x16_bf16 v[16:31], v[244:247], v[236:239], v[16:31]
	s_waitcnt vmcnt(0)
	ds_write_b128 v133, v[122:125] offset:32256
	v_mfma_f32_32x32x16_bf16 v[0:15], v[244:247], v[240:243], v[0:15]
	s_setprio 0
	s_waitcnt lgkmcnt(0)
	s_barrier
	s_setprio 1
	ds_read_b128 v[200:203], v134 offset:36864
	ds_read_b128 v[204:207], v156 offset:55296
	ds_read_b128 v[208:211], v156 offset:59904
	ds_read_b128 v[212:215], v134 offset:41472
	ds_read_b128 v[232:235], v134 offset:36896
	ds_read_b128 v[236:239], v156 offset:55328
	ds_read_b128 v[240:243], v156 offset:59936
	ds_read_b128 v[244:247], v134 offset:41504
	s_waitcnt lgkmcnt(6)
	v_mfma_f32_32x32x16_bf16 v[48:63], v[200:203], v[204:207], v[48:63]
	s_waitcnt lgkmcnt(5)
	v_mfma_f32_32x32x16_bf16 v[32:47], v[200:203], v[208:211], v[32:47]
	ds_read_b128 v[200:203], v134 offset:36928
	s_waitcnt lgkmcnt(5)
	v_mfma_f32_32x32x16_bf16 v[16:31], v[212:215], v[204:207], v[16:31]
	ds_read_b128 v[204:207], v156 offset:55360
	v_mfma_f32_32x32x16_bf16 v[0:15], v[212:215], v[208:211], v[0:15]
	ds_read_b128 v[208:211], v156 offset:59968
	ds_read_b128 v[212:215], v134 offset:41536
	s_waitcnt lgkmcnt(6)
	v_mfma_f32_32x32x16_bf16 v[48:63], v[232:235], v[236:239], v[48:63]
	s_waitcnt lgkmcnt(5)
	v_mfma_f32_32x32x16_bf16 v[32:47], v[232:235], v[240:243], v[32:47]
	ds_read_b128 v[232:235], v134 offset:36960
	s_waitcnt lgkmcnt(5)
	v_mfma_f32_32x32x16_bf16 v[16:31], v[244:247], v[236:239], v[16:31]
	ds_read_b128 v[236:239], v156 offset:55392
	v_mfma_f32_32x32x16_bf16 v[0:15], v[244:247], v[240:243], v[0:15]
	ds_read_b128 v[240:243], v156 offset:60000
	ds_read_b128 v[244:247], v134 offset:41568
	s_waitcnt lgkmcnt(6)
	v_mfma_f32_32x32x16_bf16 v[48:63], v[200:203], v[204:207], v[48:63]
	s_waitcnt lgkmcnt(5)
	v_mfma_f32_32x32x16_bf16 v[32:47], v[200:203], v[208:211], v[32:47]
	s_waitcnt lgkmcnt(4)
	v_mfma_f32_32x32x16_bf16 v[16:31], v[212:215], v[204:207], v[16:31]
	v_mfma_f32_32x32x16_bf16 v[0:15], v[212:215], v[208:211], v[0:15]
	s_waitcnt lgkmcnt(2)
	v_mfma_f32_32x32x16_bf16 v[48:63], v[232:235], v[236:239], v[48:63]
	s_waitcnt lgkmcnt(1)
	v_mfma_f32_32x32x16_bf16 v[32:47], v[232:235], v[240:243], v[32:47]
	s_waitcnt lgkmcnt(0)
	v_mfma_f32_32x32x16_bf16 v[16:31], v[244:247], v[236:239], v[16:31]
	v_mfma_f32_32x32x16_bf16 v[0:15], v[244:247], v[240:243], v[0:15]
	s_setprio 0
	s_lshl_b64 s[4:5], s[36:37], 12
	s_add_u32 s6, s40, s4
	s_addc_u32 s7, s41, s5
	s_lshl_b64 s[8:9], s[0:1], 2
	s_add_u32 s6, s6, s8
	s_addc_u32 s7, s7, s9
	v_lshl_add_u64 v[66:67], s[6:7], 0, v[64:65]
	v_add_co_u32_e32 v68, vcc, s92, v66
	s_movk_i32 s18, 0x2000
	s_nop 0
	v_addc_co_u32_e32 v69, vcc, 0, v67, vcc
	v_add_co_u32_e32 v70, vcc, s18, v66
	s_add_u32 s1, s86, s4
	s_nop 0
	v_addc_co_u32_e32 v71, vcc, 0, v67, vcc
	v_add_co_u32_e32 v72, vcc, s84, v66
	s_addc_u32 s4, s87, s5
	s_nop 0
	v_addc_co_u32_e32 v73, vcc, 0, v67, vcc
	s_mov_b32 s5, 0x8000
	v_add_co_u32_e32 v74, vcc, s5, v66
	s_mov_b32 s16, 0x9000
	s_nop 0
	v_addc_co_u32_e32 v75, vcc, 0, v67, vcc
	v_add_co_u32_e32 v76, vcc, s16, v66
	s_mov_b32 s19, 0xa000
	s_nop 0
	v_addc_co_u32_e32 v77, vcc, 0, v67, vcc
	v_add_co_u32_e32 v78, vcc, s19, v66
	s_mov_b32 s20, 0xb000
	s_nop 0
	v_addc_co_u32_e32 v79, vcc, 0, v67, vcc
	v_add_co_u32_e32 v80, vcc, s20, v66
	s_mov_b32 s21, 0x11000
	s_nop 0
	v_addc_co_u32_e32 v81, vcc, 0, v67, vcc
	v_add_co_u32_e32 v82, vcc, s12, v66
	s_mov_b32 s17, 0x12000
	s_nop 0
	v_addc_co_u32_e32 v83, vcc, 0, v67, vcc
	v_add_co_u32_e32 v84, vcc, s21, v66
	s_mov_b32 s22, 0x13000
	s_nop 0
	v_addc_co_u32_e32 v85, vcc, 0, v67, vcc
	v_add_co_u32_e32 v86, vcc, s17, v66
	s_mov_b32 s6, 0x18000
	s_nop 0
	v_addc_co_u32_e32 v87, vcc, 0, v67, vcc
	v_add_co_u32_e32 v88, vcc, s22, v66
	s_mov_b32 s23, 0x19000
	s_nop 0
	v_addc_co_u32_e32 v89, vcc, 0, v67, vcc
	v_add_co_u32_e32 v90, vcc, s6, v66
	s_mov_b32 s24, 0x1a000
	s_nop 0
	v_addc_co_u32_e32 v91, vcc, 0, v67, vcc
	v_add_co_u32_e32 v92, vcc, s23, v66
	s_mov_b32 s25, 0x1b000
	s_nop 0
	v_addc_co_u32_e32 v93, vcc, 0, v67, vcc
	v_add_co_u32_e32 v94, vcc, s24, v66
	s_mov_b32 s7, 0x20000
	s_nop 0
	v_addc_co_u32_e32 v95, vcc, 0, v67, vcc
	v_add_co_u32_e32 v96, vcc, s25, v66
	s_nop 1
	v_addc_co_u32_e32 v97, vcc, 0, v67, vcc
	s_barrier
	global_load_dword v141, v[66:67], off
	global_load_dword v140, v[70:71], off offset:-4096
	global_load_dword v139, v[70:71], off
	global_load_dword v138, v[72:73], off
	global_load_dword v129, v[76:77], off offset:-4096
	global_load_dword v128, v[76:77], off
	global_load_dword v127, v[80:81], off offset:-4096
	global_load_dword v126, v[80:81], off
	global_load_dword v125, v[84:85], off offset:-4096
	global_load_dword v124, v[84:85], off
	global_load_dword v123, v[88:89], off offset:-4096
	global_load_dword v122, v[88:89], off
	global_load_dword v121, v[92:93], off offset:-4096
	global_load_dword v120, v[92:93], off
	global_load_dword v118, v[96:97], off offset:-4096
	global_load_dword v115, v[96:97], off
	global_load_dword v119, v[66:67], off offset:128
	global_load_dword v116, v[68:69], off offset:128
	global_load_dword v113, v[70:71], off offset:128
	global_load_dword v117, v[72:73], off offset:128
	global_load_dword v112, v[74:75], off offset:128
	global_load_dword v109, v[76:77], off offset:128
	global_load_dword v106, v[78:79], off offset:128
	global_load_dword v105, v[80:81], off offset:128
	global_load_dword v102, v[82:83], off offset:128
	global_load_dword v101, v[84:85], off offset:128
	global_load_dword v98, v[86:87], off offset:128
	global_load_dword v114, v[88:89], off offset:128
	global_load_dword v110, v[90:91], off offset:128
	global_load_dword v107, v[92:93], off offset:128
	global_load_dword v104, v[94:95], off offset:128
	global_load_dword v103, v[96:97], off offset:128
	v_add_co_u32_e32 v68, vcc, s7, v66
	s_mov_b32 s26, 0x21000
	s_nop 0
	v_addc_co_u32_e32 v69, vcc, 0, v67, vcc
	v_add_co_u32_e32 v70, vcc, s26, v66
	s_mov_b32 s27, 0x22000
	s_nop 0
	v_addc_co_u32_e32 v71, vcc, 0, v67, vcc
	v_add_co_u32_e32 v78, vcc, s27, v66
	s_mov_b32 s28, 0x23000
	s_nop 0
	v_addc_co_u32_e32 v79, vcc, 0, v67, vcc
	v_add_co_u32_e32 v84, vcc, s28, v66
	s_mov_b32 s13, 0x28000
	s_nop 0
	v_addc_co_u32_e32 v85, vcc, 0, v67, vcc
	v_add_co_u32_e32 v142, vcc, s13, v66
	s_mov_b32 s29, 0x29000
	s_nop 0
	v_addc_co_u32_e32 v143, vcc, 0, v67, vcc
	v_add_co_u32_e32 v144, vcc, s29, v66
	s_mov_b32 s30, 0x2a000
	s_nop 0
	v_addc_co_u32_e32 v145, vcc, 0, v67, vcc
	v_add_co_u32_e32 v146, vcc, s30, v66
	s_mov_b32 s31, 0x2b000
	s_nop 0
	v_addc_co_u32_e32 v147, vcc, 0, v67, vcc
	v_add_co_u32_e32 v148, vcc, s31, v66
	s_mov_b32 s14, 0x30000
	s_nop 0
	v_addc_co_u32_e32 v149, vcc, 0, v67, vcc
	v_add_co_u32_e32 v150, vcc, s14, v66
	s_mov_b32 s36, 0x31000
	s_nop 0
	v_addc_co_u32_e32 v151, vcc, 0, v67, vcc
	v_add_co_u32_e32 v152, vcc, s36, v66
	s_mov_b32 s37, 0x32000
	s_nop 0
	v_addc_co_u32_e32 v153, vcc, 0, v67, vcc
	v_add_co_u32_e32 v158, vcc, s37, v66
	s_mov_b32 s38, 0x33000
	s_nop 0
	v_addc_co_u32_e32 v159, vcc, 0, v67, vcc
	v_add_co_u32_e32 v160, vcc, s38, v66
	s_mov_b32 s15, 0x38000
	s_nop 0
	v_addc_co_u32_e32 v161, vcc, 0, v67, vcc
	v_add_co_u32_e32 v162, vcc, s15, v66
	s_mov_b32 s39, 0x39000
	s_nop 0
	v_addc_co_u32_e32 v163, vcc, 0, v67, vcc
	v_add_co_u32_e32 v164, vcc, s39, v66
	s_mov_b32 s40, 0x3a000
	s_nop 0
	v_addc_co_u32_e32 v165, vcc, 0, v67, vcc
	v_add_co_u32_e32 v166, vcc, s40, v66
	s_mov_b32 s41, 0x3b000
	s_nop 0
	v_addc_co_u32_e32 v167, vcc, 0, v67, vcc
	v_add_co_u32_e32 v66, vcc, s41, v66
	global_load_dword v111, v[70:71], off offset:-4096
	global_load_dword v108, v[70:71], off
	v_addc_co_u32_e32 v67, vcc, 0, v67, vcc
	global_load_dword v100, v[84:85], off offset:-4096
	global_load_dword v99, v[84:85], off
	global_load_dword v97, v[144:145], off offset:-4096
	global_load_dword v96, v[144:145], off
	global_load_dword v95, v[148:149], off offset:-4096
	global_load_dword v94, v[148:149], off
	global_load_dword v93, v[152:153], off offset:-4096
	global_load_dword v91, v[152:153], off
	global_load_dword v88, v[160:161], off offset:-4096
	global_load_dword v86, v[160:161], off
	global_load_dword v82, v[164:165], off offset:-4096
	global_load_dword v81, v[164:165], off
	global_load_dword v77, v[66:67], off offset:-4096
	global_load_dword v75, v[66:67], off
	global_load_dword v73, v[68:69], off offset:128
	global_load_dword v92, v[70:71], off offset:128
	global_load_dword v90, v[78:79], off offset:128
	global_load_dword v89, v[84:85], off offset:128
	global_load_dword v87, v[142:143], off offset:128
	s_nop 0
	global_load_dword v85, v[144:145], off offset:128
	global_load_dword v84, v[146:147], off offset:128
	global_load_dword v83, v[148:149], off offset:128
	global_load_dword v80, v[150:151], off offset:128
	global_load_dword v79, v[152:153], off offset:128
	global_load_dword v78, v[158:159], off offset:128
	global_load_dword v76, v[160:161], off offset:128
	global_load_dword v74, v[162:163], off offset:128
	global_load_dword v72, v[164:165], off offset:128
	global_load_dword v71, v[166:167], off offset:128
	global_load_dword v70, v[66:67], off offset:128
	v_add_u32_e32 v66, s0, v157
	v_ashrrev_i32_e32 v67, 31, v66
	v_lshl_add_u64 v[66:67], v[66:67], 2, s[2:3]
	global_load_dword v248, v[66:67], off
	global_load_dword v249, v[66:67], off offset:128
	s_waitcnt vmcnt(0)
	s_add_u32 s8, s1, s8
	s_addc_u32 s9, s4, s9
	v_lshl_add_u64 v[68:69], s[8:9], 0, v[64:65]
	v_fmac_f32_e32 v141, v48, v248
	global_store_dword v[68:69], v141, off
	v_fmac_f32_e32 v140, v49, v248
	v_add_co_u32_e32 v48, vcc, s92, v68
	s_nop 1
	v_addc_co_u32_e32 v49, vcc, 0, v69, vcc
	v_add_co_u32_e32 v142, vcc, s18, v68
	s_nop 1
	v_addc_co_u32_e32 v143, vcc, 0, v69, vcc
	global_store_dword v[142:143], v140, off offset:-4096
	v_fmac_f32_e32 v139, v50, v248
	global_store_dword v[142:143], v139, off
	v_fmac_f32_e32 v138, v51, v248
	v_add_co_u32_e32 v50, vcc, s84, v68
	s_nop 1
	v_addc_co_u32_e32 v51, vcc, 0, v69, vcc
	global_store_dword v[50:51], v138, off
	v_fmac_f32_e32 v129, v52, v248
	v_add_co_u32_e32 v138, vcc, s5, v68
	s_nop 1
	v_addc_co_u32_e32 v139, vcc, 0, v69, vcc
	v_add_co_u32_e32 v140, vcc, s16, v68
	s_nop 1
	v_addc_co_u32_e32 v141, vcc, 0, v69, vcc
	global_store_dword v[140:141], v129, off offset:-4096
	v_fmac_f32_e32 v128, v53, v248
	global_store_dword v[140:141], v128, off
	v_fmac_f32_e32 v127, v54, v248
	v_add_co_u32_e32 v52, vcc, s19, v68
	s_nop 1
	v_addc_co_u32_e32 v53, vcc, 0, v69, vcc
	v_add_co_u32_e32 v128, vcc, s20, v68
	s_nop 1
	v_addc_co_u32_e32 v129, vcc, 0, v69, vcc
	global_store_dword v[128:129], v127, off offset:-4096
	v_fmac_f32_e32 v126, v55, v248
	global_store_dword v[128:129], v126, off
	v_fmac_f32_e32 v125, v56, v248
	v_add_co_u32_e32 v54, vcc, s12, v68
	s_nop 1
	v_addc_co_u32_e32 v55, vcc, 0, v69, vcc
	v_add_co_u32_e32 v126, vcc, s21, v68
	s_nop 1
	v_addc_co_u32_e32 v127, vcc, 0, v69, vcc
	global_store_dword v[126:127], v125, off offset:-4096
	v_fmac_f32_e32 v124, v57, v248
	global_store_dword v[126:127], v124, off
	v_fmac_f32_e32 v123, v58, v248
	v_add_co_u32_e32 v56, vcc, s17, v68
	s_nop 1
	v_addc_co_u32_e32 v57, vcc, 0, v69, vcc
	v_add_co_u32_e32 v124, vcc, s22, v68
	s_nop 1
	v_addc_co_u32_e32 v125, vcc, 0, v69, vcc
	global_store_dword v[124:125], v123, off offset:-4096
	v_fmac_f32_e32 v122, v59, v248
	global_store_dword v[124:125], v122, off
	v_fmac_f32_e32 v121, v60, v248
	v_add_co_u32_e32 v58, vcc, s6, v68
	s_nop 1
	v_addc_co_u32_e32 v59, vcc, 0, v69, vcc
	v_add_co_u32_e32 v122, vcc, s23, v68
	s_nop 1
	v_addc_co_u32_e32 v123, vcc, 0, v69, vcc
	global_store_dword v[122:123], v121, off offset:-4096
	v_fmac_f32_e32 v120, v61, v248
	global_store_dword v[122:123], v120, off
	v_fmac_f32_e32 v118, v62, v248
	v_add_co_u32_e32 v60, vcc, s24, v68
	s_nop 1
	v_addc_co_u32_e32 v61, vcc, 0, v69, vcc
	v_add_co_u32_e32 v120, vcc, s25, v68
	s_nop 1
	v_addc_co_u32_e32 v121, vcc, 0, v69, vcc
	global_store_dword v[120:121], v118, off offset:-4096
	v_fmac_f32_e32 v115, v63, v248
	global_store_dword v[120:121], v115, off
	v_fmac_f32_e32 v119, v32, v249
	global_store_dword v[68:69], v119, off offset:128
	v_fmac_f32_e32 v116, v33, v249
	global_store_dword v[48:49], v116, off offset:128
	v_fmac_f32_e32 v113, v34, v249
	global_store_dword v[142:143], v113, off offset:128
	v_fmac_f32_e32 v117, v35, v249
	global_store_dword v[50:51], v117, off offset:128
	v_fmac_f32_e32 v112, v36, v249
	global_store_dword v[138:139], v112, off offset:128
	v_fmac_f32_e32 v109, v37, v249
	global_store_dword v[140:141], v109, off offset:128
	v_fmac_f32_e32 v106, v38, v249
	global_store_dword v[52:53], v106, off offset:128
	v_fmac_f32_e32 v105, v39, v249
	global_store_dword v[128:129], v105, off offset:128
	v_fmac_f32_e32 v102, v40, v249
	global_store_dword v[54:55], v102, off offset:128
	v_fmac_f32_e32 v101, v41, v249
	global_store_dword v[126:127], v101, off offset:128
	v_fmac_f32_e32 v98, v42, v249
	global_store_dword v[56:57], v98, off offset:128
	v_fmac_f32_e32 v114, v43, v249
	global_store_dword v[124:125], v114, off offset:128
	v_fmac_f32_e32 v110, v44, v249
	global_store_dword v[58:59], v110, off offset:128
	v_fmac_f32_e32 v107, v45, v249
	global_store_dword v[122:123], v107, off offset:128
	v_fmac_f32_e32 v104, v46, v249
	global_store_dword v[60:61], v104, off offset:128
	v_fmac_f32_e32 v103, v47, v249
	global_store_dword v[120:121], v103, off offset:128
	v_fmac_f32_e32 v111, v16, v248
	v_add_co_u32_e32 v32, vcc, s7, v68
	s_nop 1
	v_addc_co_u32_e32 v33, vcc, 0, v69, vcc
	v_add_co_u32_e32 v34, vcc, s26, v68
	s_nop 1
	v_addc_co_u32_e32 v35, vcc, 0, v69, vcc
	global_store_dword v[34:35], v111, off offset:-4096
	v_fmac_f32_e32 v108, v17, v248
	global_store_dword v[34:35], v108, off
	v_fmac_f32_e32 v100, v18, v248
	v_add_co_u32_e32 v16, vcc, s27, v68
	s_nop 1
	v_addc_co_u32_e32 v17, vcc, 0, v69, vcc
	v_add_co_u32_e32 v36, vcc, s28, v68
	s_nop 1
	v_addc_co_u32_e32 v37, vcc, 0, v69, vcc
	global_store_dword v[36:37], v100, off offset:-4096
	v_fmac_f32_e32 v99, v19, v248
	global_store_dword v[36:37], v99, off
	v_fmac_f32_e32 v97, v20, v248
	v_add_co_u32_e32 v18, vcc, s13, v68
	s_nop 1
	v_addc_co_u32_e32 v19, vcc, 0, v69, vcc
	v_add_co_u32_e32 v38, vcc, s29, v68
	s_nop 1
	v_addc_co_u32_e32 v39, vcc, 0, v69, vcc
	global_store_dword v[38:39], v97, off offset:-4096
	v_fmac_f32_e32 v96, v21, v248
	global_store_dword v[38:39], v96, off
	v_fmac_f32_e32 v95, v22, v248
	v_add_co_u32_e32 v20, vcc, s30, v68
	s_nop 1
	v_addc_co_u32_e32 v21, vcc, 0, v69, vcc
	v_add_co_u32_e32 v40, vcc, s31, v68
	s_nop 1
	v_addc_co_u32_e32 v41, vcc, 0, v69, vcc
	global_store_dword v[40:41], v95, off offset:-4096
	v_fmac_f32_e32 v94, v23, v248
	global_store_dword v[40:41], v94, off
	v_fmac_f32_e32 v93, v24, v248
	v_add_co_u32_e32 v22, vcc, s14, v68
	s_nop 1
	v_addc_co_u32_e32 v23, vcc, 0, v69, vcc
	v_add_co_u32_e32 v42, vcc, s36, v68
	s_nop 1
	v_addc_co_u32_e32 v43, vcc, 0, v69, vcc
	global_store_dword v[42:43], v93, off offset:-4096
	v_fmac_f32_e32 v91, v25, v248
	global_store_dword v[42:43], v91, off
	v_fmac_f32_e32 v88, v26, v248
	v_add_co_u32_e32 v24, vcc, s37, v68
	s_nop 1
	v_addc_co_u32_e32 v25, vcc, 0, v69, vcc
	v_add_co_u32_e32 v44, vcc, s38, v68
	s_nop 1
	v_addc_co_u32_e32 v45, vcc, 0, v69, vcc
	global_store_dword v[44:45], v88, off offset:-4096
	v_fmac_f32_e32 v86, v27, v248
	global_store_dword v[44:45], v86, off
	v_fmac_f32_e32 v82, v28, v248
	v_add_co_u32_e32 v26, vcc, s15, v68
	s_nop 1
	v_addc_co_u32_e32 v27, vcc, 0, v69, vcc
	v_add_co_u32_e32 v46, vcc, s39, v68
	s_nop 1
	v_addc_co_u32_e32 v47, vcc, 0, v69, vcc
	global_store_dword v[46:47], v82, off offset:-4096
	v_fmac_f32_e32 v81, v29, v248
	global_store_dword v[46:47], v81, off
	v_fmac_f32_e32 v77, v30, v248
	v_add_co_u32_e32 v28, vcc, s40, v68
	s_nop 1
	v_addc_co_u32_e32 v29, vcc, 0, v69, vcc
	v_add_co_u32_e32 v48, vcc, s41, v68
	s_nop 1
	v_addc_co_u32_e32 v49, vcc, 0, v69, vcc
	global_store_dword v[48:49], v77, off offset:-4096
	v_fmac_f32_e32 v75, v31, v248
	global_store_dword v[48:49], v75, off
	v_fmac_f32_e32 v73, v0, v249
	global_store_dword v[32:33], v73, off offset:128
	v_fmac_f32_e32 v92, v1, v249
	global_store_dword v[34:35], v92, off offset:128
	v_fmac_f32_e32 v90, v2, v249
	global_store_dword v[16:17], v90, off offset:128
	v_fmac_f32_e32 v89, v3, v249
	global_store_dword v[36:37], v89, off offset:128
	v_fmac_f32_e32 v87, v4, v249
	global_store_dword v[18:19], v87, off offset:128
	v_fmac_f32_e32 v85, v5, v249
	global_store_dword v[38:39], v85, off offset:128
	v_fmac_f32_e32 v84, v6, v249
	global_store_dword v[20:21], v84, off offset:128
	v_fmac_f32_e32 v83, v7, v249
	global_store_dword v[40:41], v83, off offset:128
	v_fmac_f32_e32 v80, v8, v249
	global_store_dword v[22:23], v80, off offset:128
	v_fmac_f32_e32 v79, v9, v249
	global_store_dword v[42:43], v79, off offset:128
	v_fmac_f32_e32 v78, v10, v249
	global_store_dword v[24:25], v78, off offset:128
	v_fmac_f32_e32 v76, v11, v249
	global_store_dword v[44:45], v76, off offset:128
	v_fmac_f32_e32 v74, v12, v249
	global_store_dword v[26:27], v74, off offset:128
	v_fmac_f32_e32 v72, v13, v249
	global_store_dword v[46:47], v72, off offset:128
	v_fmac_f32_e32 v71, v14, v249
	global_store_dword v[28:29], v71, off offset:128
	v_fmac_f32_e32 v70, v15, v249
	global_store_dword v[48:49], v70, off offset:128
	s_branch .LBB0_1297

.LBB0_1434:
	s_cmp_lt_u32 s8, s2
	s_cbranch_scc1 .Lfnb_fast
	s_setprio 1
	ds_read_b128 v[200:203], v132
	ds_read_b128 v[204:207], v159 offset:18432
	ds_read_b128 v[208:211], v159 offset:23040
	ds_read_b128 v[212:215], v132 offset:4608
	ds_read_b128 v[232:235], v132 offset:32
	ds_read_b128 v[236:239], v159 offset:18464
	ds_read_b128 v[240:243], v159 offset:23072
	ds_read_b128 v[244:247], v132 offset:4640
	s_waitcnt lgkmcnt(6)
	v_mfma_f32_32x32x16_bf16 v[48:63], v[200:203], v[204:207], v[48:63]
	s_waitcnt lgkmcnt(5)
	v_mfma_f32_32x32x16_bf16 v[32:47], v[200:203], v[208:211], v[32:47]
	ds_read_b128 v[200:203], v132 offset:64
	s_waitcnt lgkmcnt(5)
	v_mfma_f32_32x32x16_bf16 v[16:31], v[212:215], v[204:207], v[16:31]
	ds_read_b128 v[204:207], v159 offset:18496
	v_mfma_f32_32x32x16_bf16 v[0:15], v[212:215], v[208:211], v[0:15]
	ds_read_b128 v[208:211], v159 offset:23104
	ds_read_b128 v[212:215], v132 offset:4672
	s_waitcnt lgkmcnt(6)
	v_mfma_f32_32x32x16_bf16 v[48:63], v[232:235], v[236:239], v[48:63]
	s_waitcnt lgkmcnt(5)
	v_mfma_f32_32x32x16_bf16 v[32:47], v[232:235], v[240:243], v[32:47]
	ds_read_b128 v[232:235], v132 offset:96
	s_waitcnt lgkmcnt(5)
	v_mfma_f32_32x32x16_bf16 v[16:31], v[244:247], v[236:239], v[16:31]
	ds_read_b128 v[236:239], v159 offset:18528
	v_mfma_f32_32x32x16_bf16 v[0:15], v[244:247], v[240:243], v[0:15]
	ds_read_b128 v[240:243], v159 offset:23136
	ds_read_b128 v[244:247], v132 offset:4704
	s_waitcnt lgkmcnt(6)
	v_mfma_f32_32x32x16_bf16 v[48:63], v[200:203], v[204:207], v[48:63]
	s_waitcnt lgkmcnt(5)
	v_mfma_f32_32x32x16_bf16 v[32:47], v[200:203], v[208:211], v[32:47]
	s_waitcnt lgkmcnt(4)
	v_mfma_f32_32x32x16_bf16 v[16:31], v[212:215], v[204:207], v[16:31]
	v_mfma_f32_32x32x16_bf16 v[0:15], v[212:215], v[208:211], v[0:15]
	s_waitcnt lgkmcnt(2)
	v_mfma_f32_32x32x16_bf16 v[48:63], v[232:235], v[236:239], v[48:63]
	s_waitcnt lgkmcnt(1)
	v_mfma_f32_32x32x16_bf16 v[32:47], v[232:235], v[240:243], v[32:47]
	s_waitcnt lgkmcnt(0)
	v_mfma_f32_32x32x16_bf16 v[16:31], v[244:247], v[236:239], v[16:31]
	v_mfma_f32_32x32x16_bf16 v[0:15], v[244:247], v[240:243], v[0:15]
	s_setprio 0
	s_add_i32 s0, s8, -3
	s_cmp_ge_u32 s0, s2
	s_cselect_b64 s[0:1], -1, 0
	s_and_b64 vcc, exec, s[0:1]
	s_cbranch_vccnz .LBB0_1436
	s_add_i32 s100, s8, -2
	s_cmp_lt_u32 s100, s2
	s_cbranch_scc1 .LfnbA_st
	s_waitcnt vmcnt(7)
	ds_write_b128 v158, v[66:69] offset:36864
	s_waitcnt vmcnt(6)
	ds_write_b128 v158, v[70:73] offset:41472
	s_waitcnt vmcnt(5)
	ds_write_b128 v158, v[74:77] offset:46080
	s_waitcnt vmcnt(4)
	ds_write_b128 v158, v[78:81] offset:50688
	s_waitcnt vmcnt(3)
	ds_write_b128 v158, v[82:85] offset:55296
	s_waitcnt vmcnt(2)
	ds_write_b128 v158, v[86:89] offset:59904
	s_waitcnt vmcnt(1)
	ds_write_b128 v158, v[90:93] offset:64512
	s_waitcnt vmcnt(0)
	ds_write_b128 v160, v[98:101] offset:32256

.LBB0_1440:
	s_andn2_b64 vcc, exec, s[0:1]
	s_cbranch_vccnz .LBB0_1446
	s_setprio 1
	ds_read_b128 v[200:203], v132 offset:36864
	ds_read_b128 v[204:207], v159 offset:55296
	ds_read_b128 v[208:211], v159 offset:59904
	ds_read_b128 v[212:215], v132 offset:41472
	ds_read_b128 v[232:235], v132 offset:36896
	ds_read_b128 v[236:239], v159 offset:55328
	ds_read_b128 v[240:243], v159 offset:59936
	ds_read_b128 v[244:247], v132 offset:41504
	s_waitcnt lgkmcnt(6)
	v_mfma_f32_32x32x16_bf16 v[48:63], v[200:203], v[204:207], v[48:63]
	s_waitcnt lgkmcnt(5)
	v_mfma_f32_32x32x16_bf16 v[32:47], v[200:203], v[208:211], v[32:47]
	ds_read_b128 v[200:203], v132 offset:36928
	s_waitcnt lgkmcnt(5)
	v_mfma_f32_32x32x16_bf16 v[16:31], v[212:215], v[204:207], v[16:31]
	ds_read_b128 v[204:207], v159 offset:55360
	v_mfma_f32_32x32x16_bf16 v[0:15], v[212:215], v[208:211], v[0:15]
	ds_read_b128 v[208:211], v159 offset:59968
	ds_read_b128 v[212:215], v132 offset:41536
	s_waitcnt lgkmcnt(6)
	v_mfma_f32_32x32x16_bf16 v[48:63], v[232:235], v[236:239], v[48:63]
	s_waitcnt lgkmcnt(5)
	v_mfma_f32_32x32x16_bf16 v[32:47], v[232:235], v[240:243], v[32:47]
	ds_read_b128 v[232:235], v132 offset:36960
	s_waitcnt lgkmcnt(5)
	v_mfma_f32_32x32x16_bf16 v[16:31], v[244:247], v[236:239], v[16:31]
	ds_read_b128 v[236:239], v159 offset:55392
	v_mfma_f32_32x32x16_bf16 v[0:15], v[244:247], v[240:243], v[0:15]
	ds_read_b128 v[240:243], v159 offset:60000
	ds_read_b128 v[244:247], v132 offset:41568
	s_waitcnt lgkmcnt(6)
	v_mfma_f32_32x32x16_bf16 v[48:63], v[200:203], v[204:207], v[48:63]
	s_waitcnt lgkmcnt(5)
	v_mfma_f32_32x32x16_bf16 v[32:47], v[200:203], v[208:211], v[32:47]
	s_waitcnt lgkmcnt(4)
	v_mfma_f32_32x32x16_bf16 v[16:31], v[212:215], v[204:207], v[16:31]
	v_mfma_f32_32x32x16_bf16 v[0:15], v[212:215], v[208:211], v[0:15]
	s_waitcnt lgkmcnt(2)
	v_mfma_f32_32x32x16_bf16 v[48:63], v[232:235], v[236:239], v[48:63]
	s_waitcnt lgkmcnt(1)
	v_mfma_f32_32x32x16_bf16 v[32:47], v[232:235], v[240:243], v[32:47]
	s_waitcnt lgkmcnt(0)
	v_mfma_f32_32x32x16_bf16 v[16:31], v[244:247], v[236:239], v[16:31]
	v_mfma_f32_32x32x16_bf16 v[0:15], v[244:247], v[240:243], v[0:15]
	s_setprio 0
	s_add_i32 s0, s8, -2
	s_cmp_ge_u32 s0, s2
	s_cbranch_scc1 .LBB0_1443
	s_add_i32 s100, s8, -1
	s_cmp_lt_u32 s100, s2
	s_cbranch_scc1 .LfnbB_st
	s_waitcnt vmcnt(7)
	ds_write_b128 v158, v[94:97]
	s_waitcnt vmcnt(6)
	ds_write_b128 v158, v[102:105] offset:4608
	s_waitcnt vmcnt(5)
	ds_write_b128 v158, v[106:109] offset:9216
	s_waitcnt vmcnt(4)
	ds_write_b128 v158, v[110:113] offset:13824
	s_waitcnt vmcnt(3)
	ds_write_b128 v158, v[114:117] offset:18432
	s_waitcnt vmcnt(2)
	ds_write_b128 v158, v[118:121] offset:23040
	s_waitcnt vmcnt(1)
	ds_write_b128 v158, v[122:125] offset:27648
	s_waitcnt vmcnt(0)
	ds_write_b128 v158, v[126:129] offset:32256

.LfnbA_st:
	s_waitcnt vmcnt(15)
	ds_write_b128 v158, v[66:69] offset:36864
	s_waitcnt vmcnt(14)
	ds_write_b128 v158, v[70:73] offset:41472
	s_waitcnt vmcnt(13)
	ds_write_b128 v158, v[74:77] offset:46080
	s_waitcnt vmcnt(12)
	ds_write_b128 v158, v[78:81] offset:50688
	s_waitcnt vmcnt(11)
	ds_write_b128 v158, v[82:85] offset:55296
	s_waitcnt vmcnt(10)
	ds_write_b128 v158, v[86:89] offset:59904
	s_waitcnt vmcnt(9)
	ds_write_b128 v158, v[90:93] offset:64512
	s_waitcnt vmcnt(8)
	ds_write_b128 v160, v[98:101] offset:32256
	s_add_i32 s9, s8, -1
	s_cmp_ge_u32 s9, s2
	s_cbranch_scc1 .LBB0_1438
	v_lshl_add_u64 v[66:67], v[142:143], 0, v[134:135]
	v_lshl_add_u64 v[70:71], v[146:147], 0, v[134:135]
	v_lshl_add_u64 v[74:75], v[148:149], 0, v[134:135]
	v_lshl_add_u64 v[78:79], v[150:151], 0, v[134:135]
	v_lshl_add_u64 v[82:83], v[144:145], 0, v[134:135]
	v_lshl_add_u64 v[86:87], v[152:153], 0, v[134:135]
	v_lshl_add_u64 v[90:91], v[154:155], 0, v[134:135]
	v_lshl_add_u64 v[98:99], v[156:157], 0, v[134:135]
	global_load_dwordx4 v[66:69], v[66:67], off offset:384
	s_nop 0
	global_load_dwordx4 v[70:73], v[70:71], off offset:384
	s_nop 0
	global_load_dwordx4 v[74:77], v[74:75], off offset:384
	s_nop 0
	global_load_dwordx4 v[78:81], v[78:79], off offset:384
	s_nop 0
	global_load_dwordx4 v[82:85], v[82:83], off offset:384
	s_nop 0
	global_load_dwordx4 v[86:89], v[86:87], off offset:384
	s_nop 0
	global_load_dwordx4 v[90:93], v[90:91], off offset:384
	s_nop 0
	global_load_dwordx4 v[98:101], v[98:99], off offset:384
	s_branch .LBB0_1438
.LfnbB_st:
	s_waitcnt vmcnt(15)
	ds_write_b128 v158, v[94:97]
	s_waitcnt vmcnt(14)
	ds_write_b128 v158, v[102:105] offset:4608
	s_waitcnt vmcnt(13)
	ds_write_b128 v158, v[106:109] offset:9216
	s_waitcnt vmcnt(12)
	ds_write_b128 v158, v[110:113] offset:13824
	s_waitcnt vmcnt(11)
	ds_write_b128 v158, v[114:117] offset:18432
	s_waitcnt vmcnt(10)
	ds_write_b128 v158, v[118:121] offset:23040
	s_waitcnt vmcnt(9)
	ds_write_b128 v158, v[122:125] offset:27648
	s_waitcnt vmcnt(8)
	ds_write_b128 v158, v[126:129] offset:32256
	s_cmp_ge_u32 s8, s2
	s_cbranch_scc1 .LBB0_1445
	v_lshl_add_u64 v[94:95], v[142:143], 0, v[134:135]
	v_lshl_add_u64 v[102:103], v[146:147], 0, v[134:135]
	v_lshl_add_u64 v[106:107], v[148:149], 0, v[134:135]
	v_lshl_add_u64 v[110:111], v[150:151], 0, v[134:135]
	v_lshl_add_u64 v[114:115], v[144:145], 0, v[134:135]
	v_lshl_add_u64 v[118:119], v[152:153], 0, v[134:135]
	v_lshl_add_u64 v[122:123], v[154:155], 0, v[134:135]
	v_lshl_add_u64 v[126:127], v[156:157], 0, v[134:135]
	global_load_dwordx4 v[94:97], v[94:95], off offset:512
	s_nop 0
	global_load_dwordx4 v[102:105], v[102:103], off offset:512
	s_nop 0
	global_load_dwordx4 v[106:109], v[106:107], off offset:512
	s_nop 0
	global_load_dwordx4 v[110:113], v[110:111], off offset:512
	s_nop 0
	global_load_dwordx4 v[114:117], v[114:115], off offset:512
	s_nop 0
	global_load_dwordx4 v[118:121], v[118:119], off offset:512
	s_nop 0
	global_load_dwordx4 v[122:125], v[122:123], off offset:512
	s_nop 0
	global_load_dwordx4 v[126:129], v[126:127], off offset:512
	s_branch .LBB0_1445
.Lfnb_fast:
	s_setprio 1
	ds_read_b128 v[200:203], v132
	ds_read_b128 v[204:207], v159 offset:18432
	ds_read_b128 v[208:211], v159 offset:23040
	ds_read_b128 v[212:215], v132 offset:4608
	ds_read_b128 v[232:235], v132 offset:32
	ds_read_b128 v[236:239], v159 offset:18464
	ds_read_b128 v[240:243], v159 offset:23072
	ds_read_b128 v[244:247], v132 offset:4640
	s_waitcnt lgkmcnt(6)
	v_mfma_f32_32x32x16_bf16 v[48:63], v[200:203], v[204:207], v[48:63]
	s_waitcnt lgkmcnt(5)
	v_mfma_f32_32x32x16_bf16 v[32:47], v[200:203], v[208:211], v[32:47]
	s_waitcnt vmcnt(15)
	ds_write_b128 v158, v[66:69] offset:36864
	s_waitcnt vmcnt(14)
	ds_write_b128 v158, v[70:73] offset:41472
	ds_read_b128 v[200:203], v132 offset:64
	s_waitcnt lgkmcnt(7)
	v_mfma_f32_32x32x16_bf16 v[16:31], v[212:215], v[204:207], v[16:31]
	s_waitcnt vmcnt(13)
	ds_write_b128 v158, v[74:77] offset:46080
	ds_read_b128 v[204:207], v159 offset:18496
	v_mfma_f32_32x32x16_bf16 v[0:15], v[212:215], v[208:211], v[0:15]
	s_waitcnt vmcnt(12)
	ds_write_b128 v158, v[78:81] offset:50688
	ds_read_b128 v[208:211], v159 offset:23104
	ds_read_b128 v[212:215], v132 offset:4672
	s_waitcnt lgkmcnt(10)
	v_mfma_f32_32x32x16_bf16 v[48:63], v[232:235], v[236:239], v[48:63]
	s_waitcnt vmcnt(11)
	ds_write_b128 v158, v[82:85] offset:55296
	s_waitcnt lgkmcnt(10)
	v_mfma_f32_32x32x16_bf16 v[32:47], v[232:235], v[240:243], v[32:47]
	s_waitcnt vmcnt(10)
	ds_write_b128 v158, v[86:89] offset:59904
	ds_read_b128 v[232:235], v132 offset:96
	s_waitcnt lgkmcnt(11)
	v_mfma_f32_32x32x16_bf16 v[16:31], v[244:247], v[236:239], v[16:31]
	s_waitcnt vmcnt(9)
	ds_write_b128 v158, v[90:93] offset:64512
	ds_read_b128 v[236:239], v159 offset:18528
	v_mfma_f32_32x32x16_bf16 v[0:15], v[244:247], v[240:243], v[0:15]
	s_waitcnt vmcnt(8)
	ds_write_b128 v160, v[98:101] offset:32256
	ds_read_b128 v[240:243], v159 offset:23136
	ds_read_b128 v[244:247], v132 offset:4704
	s_waitcnt lgkmcnt(11)
	v_mfma_f32_32x32x16_bf16 v[48:63], v[200:203], v[204:207], v[48:63]
	v_lshl_add_u64 v[66:67], v[142:143], 0, v[134:135]
	global_load_dwordx4 v[66:69], v[66:67], off offset:384
	s_waitcnt lgkmcnt(9)
	v_mfma_f32_32x32x16_bf16 v[32:47], v[200:203], v[208:211], v[32:47]
	v_lshl_add_u64 v[70:71], v[146:147], 0, v[134:135]
	global_load_dwordx4 v[70:73], v[70:71], off offset:384
	s_waitcnt lgkmcnt(8)
	v_mfma_f32_32x32x16_bf16 v[16:31], v[212:215], v[204:207], v[16:31]
	v_lshl_add_u64 v[74:75], v[148:149], 0, v[134:135]
	global_load_dwordx4 v[74:77], v[74:75], off offset:384
	v_mfma_f32_32x32x16_bf16 v[0:15], v[212:215], v[208:211], v[0:15]
	v_lshl_add_u64 v[78:79], v[150:151], 0, v[134:135]
	global_load_dwordx4 v[78:81], v[78:79], off offset:384
	s_waitcnt lgkmcnt(3)
	v_mfma_f32_32x32x16_bf16 v[48:63], v[232:235], v[236:239], v[48:63]
	v_lshl_add_u64 v[82:83], v[144:145], 0, v[134:135]
	global_load_dwordx4 v[82:85], v[82:83], off offset:384
	s_waitcnt lgkmcnt(1)
	v_mfma_f32_32x32x16_bf16 v[32:47], v[232:235], v[240:243], v[32:47]
	v_lshl_add_u64 v[86:87], v[152:153], 0, v[134:135]
	global_load_dwordx4 v[86:89], v[86:87], off offset:384
	s_waitcnt lgkmcnt(0)
	v_mfma_f32_32x32x16_bf16 v[16:31], v[244:247], v[236:239], v[16:31]
	v_lshl_add_u64 v[90:91], v[154:155], 0, v[134:135]
	global_load_dwordx4 v[90:93], v[90:91], off offset:384
	v_mfma_f32_32x32x16_bf16 v[0:15], v[244:247], v[240:243], v[0:15]
	v_lshl_add_u64 v[98:99], v[156:157], 0, v[134:135]
	global_load_dwordx4 v[98:101], v[98:99], off offset:384
	s_setprio 0
	s_waitcnt lgkmcnt(0)
	s_barrier
	s_setprio 1
	ds_read_b128 v[200:203], v132 offset:36864
	ds_read_b128 v[204:207], v159 offset:55296
	ds_read_b128 v[208:211], v159 offset:59904
	ds_read_b128 v[212:215], v132 offset:41472
	ds_read_b128 v[232:235], v132 offset:36896
	ds_read_b128 v[236:239], v159 offset:55328
	ds_read_b128 v[240:243], v159 offset:59936
	ds_read_b128 v[244:247], v132 offset:41504
	s_waitcnt lgkmcnt(6)
	v_mfma_f32_32x32x16_bf16 v[48:63], v[200:203], v[204:207], v[48:63]
	s_waitcnt lgkmcnt(5)
	v_mfma_f32_32x32x16_bf16 v[32:47], v[200:203], v[208:211], v[32:47]
	s_waitcnt vmcnt(15)
	ds_write_b128 v158, v[94:97]
	s_waitcnt vmcnt(14)
	ds_write_b128 v158, v[102:105] offset:4608
	ds_read_b128 v[200:203], v132 offset:36928
	s_waitcnt lgkmcnt(7)
	v_mfma_f32_32x32x16_bf16 v[16:31], v[212:215], v[204:207], v[16:31]
	s_waitcnt vmcnt(13)
	ds_write_b128 v158, v[106:109] offset:9216
	ds_read_b128 v[204:207], v159 offset:55360
	v_mfma_f32_32x32x16_bf16 v[0:15], v[212:215], v[208:211], v[0:15]
	s_waitcnt vmcnt(12)
	ds_write_b128 v158, v[110:113] offset:13824
	ds_read_b128 v[208:211], v159 offset:59968
	ds_read_b128 v[212:215], v132 offset:41536
	s_waitcnt lgkmcnt(10)
	v_mfma_f32_32x32x16_bf16 v[48:63], v[232:235], v[236:239], v[48:63]
	s_waitcnt vmcnt(11)
	ds_write_b128 v158, v[114:117] offset:18432
	s_waitcnt lgkmcnt(10)
	v_mfma_f32_32x32x16_bf16 v[32:47], v[232:235], v[240:243], v[32:47]
	s_waitcnt vmcnt(10)
	ds_write_b128 v158, v[118:121] offset:23040
	ds_read_b128 v[232:235], v132 offset:36960
	s_waitcnt lgkmcnt(11)
	v_mfma_f32_32x32x16_bf16 v[16:31], v[244:247], v[236:239], v[16:31]
	s_waitcnt vmcnt(9)
	ds_write_b128 v158, v[122:125] offset:27648
	ds_read_b128 v[236:239], v159 offset:55392
	v_mfma_f32_32x32x16_bf16 v[0:15], v[244:247], v[240:243], v[0:15]
	s_waitcnt vmcnt(8)
	ds_write_b128 v158, v[126:129] offset:32256
	ds_read_b128 v[240:243], v159 offset:60000
	ds_read_b128 v[244:247], v132 offset:41568
	s_waitcnt lgkmcnt(11)
	v_mfma_f32_32x32x16_bf16 v[48:63], v[200:203], v[204:207], v[48:63]
	v_lshl_add_u64 v[94:95], v[142:143], 0, v[134:135]
	global_load_dwordx4 v[94:97], v[94:95], off offset:512
	s_waitcnt lgkmcnt(9)
	v_mfma_f32_32x32x16_bf16 v[32:47], v[200:203], v[208:211], v[32:47]
	v_lshl_add_u64 v[102:103], v[146:147], 0, v[134:135]
	global_load_dwordx4 v[102:105], v[102:103], off offset:512
	s_waitcnt lgkmcnt(8)
	v_mfma_f32_32x32x16_bf16 v[16:31], v[212:215], v[204:207], v[16:31]
	v_lshl_add_u64 v[106:107], v[148:149], 0, v[134:135]
	global_load_dwordx4 v[106:109], v[106:107], off offset:512
	v_mfma_f32_32x32x16_bf16 v[0:15], v[212:215], v[208:211], v[0:15]
	v_lshl_add_u64 v[110:111], v[150:151], 0, v[134:135]
	global_load_dwordx4 v[110:113], v[110:111], off offset:512
	s_waitcnt lgkmcnt(3)
	v_mfma_f32_32x32x16_bf16 v[48:63], v[232:235], v[236:239], v[48:63]
	v_lshl_add_u64 v[114:115], v[144:145], 0, v[134:135]
	global_load_dwordx4 v[114:117], v[114:115], off offset:512
	s_waitcnt lgkmcnt(1)
	v_mfma_f32_32x32x16_bf16 v[32:47], v[232:235], v[240:243], v[32:47]
	v_lshl_add_u64 v[118:119], v[152:153], 0, v[134:135]
	global_load_dwordx4 v[118:121], v[118:119], off offset:512
	s_waitcnt lgkmcnt(0)
	v_mfma_f32_32x32x16_bf16 v[16:31], v[244:247], v[236:239], v[16:31]
	v_lshl_add_u64 v[122:123], v[154:155], 0, v[134:135]
	global_load_dwordx4 v[122:125], v[122:123], off offset:512
	v_mfma_f32_32x32x16_bf16 v[0:15], v[244:247], v[240:243], v[0:15]
	v_lshl_add_u64 v[126:127], v[156:157], 0, v[134:135]
	global_load_dwordx4 v[126:129], v[126:127], off offset:512
	s_setprio 0
	s_add_i32 s3, s3, 2
	s_waitcnt lgkmcnt(0)
	s_barrier
	s_mov_b64 s[12:13], 0x100
	v_lshl_add_u64 v[142:143], v[142:143], 0, s[12:13]
	v_lshl_add_u64 v[146:147], v[146:147], 0, s[12:13]
	v_lshl_add_u64 v[148:149], v[148:149], 0, s[12:13]
	v_lshl_add_u64 v[150:151], v[150:151], 0, s[12:13]
	v_lshl_add_u64 v[144:145], v[144:145], 0, s[12:13]
	v_lshl_add_u64 v[152:153], v[152:153], 0, s[12:13]
	v_lshl_add_u64 v[154:155], v[154:155], 0, s[12:13]
	v_lshl_add_u64 v[156:157], v[156:157], 0, s[12:13]
	s_add_i32 s8, s8, 2
	s_branch .LBB0_1434

	.amdhsa_kernel _Z4mega6Params
		.amdhsa_group_segment_fixed_size 73744
		.amdhsa_private_segment_fixed_size 0
		.amdhsa_kernarg_size 648
		.amdhsa_user_sgpr_count 2
		.amdhsa_user_sgpr_dispatch_ptr 0
		.amdhsa_user_sgpr_queue_ptr 0
		.amdhsa_user_sgpr_kernarg_segment_ptr 1
		.amdhsa_user_sgpr_dispatch_id 0
		.amdhsa_user_sgpr_kernarg_preload_length 0
		.amdhsa_user_sgpr_kernarg_preload_offset 0
		.amdhsa_user_sgpr_private_segment_size 0
		.amdhsa_uses_dynamic_stack 0
		.amdhsa_enable_private_segment 0
		.amdhsa_system_sgpr_workgroup_id_x 1
		.amdhsa_system_sgpr_workgroup_id_y 0
		.amdhsa_system_sgpr_workgroup_id_z 0
		.amdhsa_system_sgpr_workgroup_info 0
		.amdhsa_system_vgpr_workitem_id 2
		.amdhsa_next_free_vgpr 256
		.amdhsa_next_free_sgpr 102
		.amdhsa_accum_offset 256
		.amdhsa_reserve_vcc 1
		.amdhsa_float_round_mode_32 0
		.amdhsa_float_round_mode_16_64 0
		.amdhsa_float_denorm_mode_32 3
		.amdhsa_float_denorm_mode_16_64 3
		.amdhsa_dx10_clamp 1
		.amdhsa_ieee_mode 1
		.amdhsa_fp16_overflow 0
		.amdhsa_tg_split 0
		.amdhsa_exception_fp_ieee_invalid_op 0
		.amdhsa_exception_fp_denorm_src 0
		.amdhsa_exception_fp_ieee_div_zero 0
		.amdhsa_exception_fp_ieee_overflow 0
		.amdhsa_exception_fp_ieee_underflow 0
		.amdhsa_exception_fp_ieee_inexact 0
		.amdhsa_exception_int_div_zero 0
	.end_amdhsa_kernel

amdhsa.kernels:
  - .agpr_count:     0
    .args:
      - .offset:         0
        .size:           392
        .value_kind:     by_value
      - .offset:         392
        .size:           4
        .value_kind:     hidden_block_count_x
      - .offset:         396
        .size:           4
        .value_kind:     hidden_block_count_y
      - .offset:         400
        .size:           4
        .value_kind:     hidden_block_count_z
      - .offset:         404
        .size:           2
        .value_kind:     hidden_group_size_x
      - .offset:         406
        .size:           2
        .value_kind:     hidden_group_size_y
      - .offset:         408
        .size:           2
        .value_kind:     hidden_group_size_z
      - .offset:         410
        .size:           2
        .value_kind:     hidden_remainder_x
      - .offset:         412
        .size:           2
        .value_kind:     hidden_remainder_y
      - .offset:         414
        .size:           2
        .value_kind:     hidden_remainder_z
      - .offset:         432
        .size:           8
        .value_kind:     hidden_global_offset_x
      - .offset:         440
        .size:           8
        .value_kind:     hidden_global_offset_y
      - .offset:         448
        .size:           8
        .value_kind:     hidden_global_offset_z
      - .offset:         456
        .size:           2
        .value_kind:     hidden_grid_dims
      - .offset:         480
        .size:           8
        .value_kind:     hidden_multigrid_sync_arg
    .group_segment_fixed_size: 73744
    .kernarg_segment_align: 8
    .kernarg_segment_size: 648
    .language:       OpenCL C
    .language_version:
      - 2
      - 0
    .max_flat_workgroup_size: 256
    .name:           _Z4mega6Params
    .private_segment_fixed_size: 0
    .sgpr_count:     108
    .sgpr_spill_count: 219
    .symbol:         _Z4mega6Params.kd
    .uniform_work_group_size: 1
    .uses_dynamic_stack: false
    .vgpr_count:     256
    .vgpr_spill_count: 0
    .wavefront_size: 64
